# v31 with the write-through stores at agent scope (sc1) instead of system scope (sc0 sc1)
# baseline (speedup 1.0000x reference)
; #define LAS __attribute__((address_space(3)))
; __device__ __forceinline__ unsigned pk2(float lo, float hi) { return f2bf(lo) | (f2bf(hi) << 16); }
; __device__ __forceinline__ void tr_item(const float* W, int K, int N, const float* kscale, bf16* WT, int dst_row0, LAS float* scr, int k0, int n0, int lane) {
;     ...
;     for (int j = 0; j < 4; ++j) { const int n = (lane >> 3) + 8 * j; const LAS float* s = scr + (8 * c) * 33 + n;
;         u32x4 o; o.x = pk2(s[0 * 33], s[1 * 33]); o.y = pk2(s[2 * 33], s[3 * 33]); o.z = pk2(s[4 * 33], s[5 * 33]); o.w = pk2(s[6 * 33], s[7 * 33]);
;         *(u32x4*)(WT + (size_t)(dst_row0 + n) * K + k0 + 8 * c) = o; }
.Lwq_nks_2:
	v_cvt_pk_bf16_f32 v58, v26, v28
	v_cvt_pk_bf16_f32 v59, v30, v32
	v_cvt_pk_bf16_f32 v60, v34, v36
	v_cvt_pk_bf16_f32 v61, v38, v40
	v_cvt_pk_bf16_f32 v62, v27, v29
	v_cvt_pk_bf16_f32 v63, v31, v33
	v_cvt_pk_bf16_f32 v64, v35, v37
	v_cvt_pk_bf16_f32 v65, v39, v41
	v_cvt_pk_bf16_f32 v66, v42, v44
	v_cvt_pk_bf16_f32 v67, v46, v48
	v_cvt_pk_bf16_f32 v68, v50, v52
	v_cvt_pk_bf16_f32 v69, v54, v56
	v_cvt_pk_bf16_f32 v70, v43, v45
	v_cvt_pk_bf16_f32 v71, v47, v49
	v_cvt_pk_bf16_f32 v72, v51, v53
	v_cvt_pk_bf16_f32 v73, v55, v57
	global_store_dwordx4 v22, v[58:61], s[68:69] sc1
	global_store_dwordx4 v23, v[62:65], s[68:69] sc1
	global_store_dwordx4 v24, v[66:69], s[68:69] sc1
	global_store_dwordx4 v25, v[70:73], s[68:69] sc1
	s_cmp_lt_u32 s82, 0x5100
	s_cbranch_scc0 .LBB0_81
	s_mov_b32 s83, s82

; #define LAS __attribute__((address_space(3)))
; __device__ __forceinline__ unsigned pk2(float lo, float hi) { return f2bf(lo) | (f2bf(hi) << 16); }
; __device__ __forceinline__ void tr_item(const float* W, int K, int N, const float* kscale, bf16* WT, int dst_row0, LAS float* scr, int k0, int n0, int lane) {
;     ...
;     for (int j = 0; j < 4; ++j) { const int n = (lane >> 3) + 8 * j; const LAS float* s = scr + (8 * c) * 33 + n;
;         u32x4 o; o.x = pk2(s[0 * 33], s[1 * 33]); o.y = pk2(s[2 * 33], s[3 * 33]); o.z = pk2(s[4 * 33], s[5 * 33]); o.w = pk2(s[6 * 33], s[7 * 33]);
;         *(u32x4*)(WT + (size_t)(dst_row0 + n) * K + k0 + 8 * c) = o; }
; __device__ __forceinline__ void prologue(const Args& a, LAS unsigned char* lds, int wave, int lane) {
;     ...
;     for (int it = gw; it < DEPTH * I_L; it += NGW) {
.Lwq_nks_4:
	v_cvt_pk_bf16_f32 v58, v26, v28
	v_cvt_pk_bf16_f32 v59, v30, v32
	v_cvt_pk_bf16_f32 v60, v34, v36
	v_cvt_pk_bf16_f32 v61, v38, v40
	v_cvt_pk_bf16_f32 v62, v27, v29
	v_cvt_pk_bf16_f32 v63, v31, v33
	v_cvt_pk_bf16_f32 v64, v35, v37
	v_cvt_pk_bf16_f32 v65, v39, v41
	v_cvt_pk_bf16_f32 v66, v42, v44
	v_cvt_pk_bf16_f32 v67, v46, v48
	v_cvt_pk_bf16_f32 v68, v50, v52
	v_cvt_pk_bf16_f32 v69, v54, v56
	v_cvt_pk_bf16_f32 v70, v43, v45
	v_cvt_pk_bf16_f32 v71, v47, v49
	v_cvt_pk_bf16_f32 v72, v51, v53
	v_cvt_pk_bf16_f32 v73, v55, v57
	global_store_dwordx4 v22, v[58:61], s[78:79] sc1
	global_store_dwordx4 v23, v[62:65], s[78:79] sc1
	global_store_dwordx4 v24, v[66:69], s[78:79] sc1
	global_store_dwordx4 v25, v[70:73], s[78:79] sc1
	s_cmp_lt_u32 s82, 0x5100
	s_cbranch_scc0 .LBB0_81
	s_mov_b32 s83, s82
	s_branch .Lwq_top0

; __device__ __forceinline__ unsigned f2bf(float f) { unsigned u = __builtin_bit_cast(unsigned, f); return (u + 0x7fffu + ((u >> 16) & 1u)) >> 16; }
; __device__ __forceinline__ void prologue(const Args& a, LAS unsigned char* lds, int wave, int lane) {
;     ...
;     { const float* wsrc = a.in[7]; bf16* wsb = (bf16*)(ws + WS_WSB);
;       for (int e = gt; e < DEPTH * 8 * 128 * 128; e += NGT) { const int s = e & 127, t = (e >> 7) & 127; const float v = ((t >> 6) >= (s >> 6)) ? wsrc[e] : 0.f; wsb[e] = (bf16)f2bf(v); } }
.LBB0_83:
	s_or_b64 exec, exec, s[26:27]
	s_waitcnt vmcnt(0)
	v_bfe_u32 v9, v8, 16, 1
	v_add_u32_e32 v1, s2, v1
	v_add3_u32 v8, v8, v9, s3
	v_cmp_lt_i32_e64 s[0:1], s29, v1
	global_store_short_d16_hi v[6:7], v8, off sc1
	v_lshl_add_u64 v[4:5], v[4:5], 0, s[20:21]
	s_or_b64 s[24:25], s[0:1], s[24:25]
	v_lshl_add_u64 v[6:7], v[6:7], 0, s[22:23]
	s_andn2_b64 exec, exec, s[24:25]
	s_cbranch_execz .LBB0_86

; __device__ __forceinline__ void prologue(const Args& a, LAS unsigned char* lds, int wave, int lane) {
;     ...
;     { u64* rs = (u64*)(ws + WS_ROWSS) + M; for (int e = gt; e < 8 * M; e += NGT) rs[e] = 0ull; }
.LBB0_88:
	v_add_u32_e32 v2, s2, v2
	v_cmp_lt_i32_e32 vcc, s3, v2
	global_store_dwordx2 v[4:5], v[6:7], off sc1
	s_or_b64 s[20:21], vcc, s[20:21]
	v_lshl_add_u64 v[4:5], v[4:5], 0, s[4:5]
	s_andn2_b64 exec, exec, s[20:21]
	s_cbranch_execnz .LBB0_88

; __device__ __forceinline__ u64 ss_fix(float s) { return (u64)(s * 1099511627776.0f); }
; __device__ __forceinline__ unsigned pk2(float lo, float hi) { return f2bf(lo) | (f2bf(hi) << 16); }
; __device__ __forceinline__ void prologue(const Args& a, LAS unsigned char* lds, int wave, int lane) {
;     ...
;           const f32x4* xr = (const f32x4*)(x + (size_t)m * D) + lane; f32x4 v[2][4]; float s[2] = {0.f, 0.f};
; #pragma unroll
;           for (int r = 0; r < 2; ++r)
; #pragma unroll
;               for (int j = 0; j < 4; ++j) v[r][j] = xr[r * (D / 4) + 64 * j];
; #pragma unroll
;           for (int r = 0; r < 2; ++r) {
; #pragma unroll
;               for (int j = 0; j < 4; ++j) s[r] += (v[r][j][0] * v[r][j][0] + v[r][j][1] * v[r][j][1]) + (v[r][j][2] * v[r][j][2] + v[r][j][3] * v[r][j][3]);
;               s[r] = wave_sum(s[r]); if (lane == 0) rs0[m + r] = ss_fix(s[r]);
;               u32x2* o = (u32x2*)(XN + (size_t)(m + r) * D) + lane;
; #pragma unroll
;               for (int j = 0; j < 4; ++j) { u32x2 w; w.x = pk2(v[r][j][0], v[r][j][1]); w.y = pk2(v[r][j][2], v[r][j][3]); o[64 * j] = w; }
.Lxn_a_p:
	s_lshl_b32 s4, s0, 11
	s_add_u32 s4, s22, s4
	s_addc_u32 s5, s23, 0
	s_lshl_b32 s20, s0, 3
	s_add_u32 s20, s24, s20
	s_addc_u32 s21, s25, 0
	v_mul_f32_e32 v60, v8, v8
	v_fmac_f32_e32 v60, v9, v9
	v_mul_f32_e32 v61, v10, v10
	v_fmac_f32_e32 v61, v11, v11
	v_add_f32_e32 v60, v60, v61
	v_mov_b32_e32 v62, v60
	v_mul_f32_e32 v60, v12, v12
	v_fmac_f32_e32 v60, v13, v13
	v_mul_f32_e32 v61, v14, v14
	v_fmac_f32_e32 v61, v15, v15
	v_add_f32_e32 v60, v60, v61
	v_add_f32_e32 v62, v62, v60
	v_mul_f32_e32 v60, v16, v16
	v_fmac_f32_e32 v60, v17, v17
	v_mul_f32_e32 v61, v18, v18
	v_fmac_f32_e32 v61, v19, v19
	v_add_f32_e32 v60, v60, v61
	v_add_f32_e32 v62, v62, v60
	v_mul_f32_e32 v60, v20, v20
	v_fmac_f32_e32 v60, v21, v21
	v_mul_f32_e32 v61, v22, v22
	v_fmac_f32_e32 v61, v23, v23
	v_add_f32_e32 v60, v60, v61
	v_add_f32_e32 v62, v62, v60
	s_nop 1
	v_add_f32_dpp v62, v62, v62 quad_perm:[1,0,3,2] row_mask:0xf bank_mask:0xf
	s_nop 1
	v_add_f32_dpp v62, v62, v62 quad_perm:[2,3,0,1] row_mask:0xf bank_mask:0xf
	s_nop 1
	v_add_f32_dpp v62, v62, v62 row_half_mirror row_mask:0xf bank_mask:0xf
	s_nop 1
	v_add_f32_dpp v62, v62, v62 row_mirror row_mask:0xf bank_mask:0xf
	s_nop 1
	v_readlane_b32 s38, v62, 0
	v_readlane_b32 s39, v62, 16
	v_readlane_b32 s40, v62, 32
	v_readlane_b32 s41, v62, 48
	s_nop 2
	v_mov_b32_e32 v63, s38
	v_add_f32_e32 v63, s39, v63
	v_add_f32_e32 v63, s40, v63
	v_add_f32_e32 v63, s41, v63
	v_mul_f32_e32 v64, 0x53800000, v63
	v_trunc_f32_e32 v64, v64
	v_mul_f32_e32 v65, 0x2f800000, v64
	v_floor_f32_e32 v65, v65
	v_fmac_f32_e32 v64, 0xcf800000, v65
	v_cvt_u32_f32_e32 v64, v64
	v_cvt_u32_f32_e32 v65, v65
	s_mov_b64 exec, 1
	global_store_dwordx2 v1, v[64:65], s[20:21] sc1
	s_mov_b64 exec, -1
	v_cvt_pk_bf16_f32 v66, v8, v9
	v_cvt_pk_bf16_f32 v67, v10, v11
	global_store_dwordx2 v3, v[66:67], s[4:5] offset:0 sc1
	v_cvt_pk_bf16_f32 v68, v12, v13
	v_cvt_pk_bf16_f32 v69, v14, v15
	global_store_dwordx2 v3, v[68:69], s[4:5] offset:512 sc1
	v_cvt_pk_bf16_f32 v70, v16, v17
	v_cvt_pk_bf16_f32 v71, v18, v19
	global_store_dwordx2 v3, v[70:71], s[4:5] offset:1024 sc1
	v_cvt_pk_bf16_f32 v72, v20, v21
	v_cvt_pk_bf16_f32 v73, v22, v23
	global_store_dwordx2 v3, v[72:73], s[4:5] offset:1536 sc1
	s_add_u32 s0, s0, s1
	s_cmp_lt_u32 s0, 0x8000
	s_cbranch_scc0 .LBB0_98

; __device__ __forceinline__ u64 ss_fix(float s) { return (u64)(s * 1099511627776.0f); }
; __device__ __forceinline__ unsigned pk2(float lo, float hi) { return f2bf(lo) | (f2bf(hi) << 16); }
; __device__ __forceinline__ void prologue(const Args& a, LAS unsigned char* lds, int wave, int lane) {
;     ...
;           const f32x4* xr = (const f32x4*)(x + (size_t)m * D) + lane; f32x4 v[2][4]; float s[2] = {0.f, 0.f};
; #pragma unroll
;           for (int r = 0; r < 2; ++r)
; #pragma unroll
;               for (int j = 0; j < 4; ++j) v[r][j] = xr[r * (D / 4) + 64 * j];
; #pragma unroll
;           for (int r = 0; r < 2; ++r) {
; #pragma unroll
;               for (int j = 0; j < 4; ++j) s[r] += (v[r][j][0] * v[r][j][0] + v[r][j][1] * v[r][j][1]) + (v[r][j][2] * v[r][j][2] + v[r][j][3] * v[r][j][3]);
;               s[r] = wave_sum(s[r]); if (lane == 0) rs0[m + r] = ss_fix(s[r]);
;               u32x2* o = (u32x2*)(XN + (size_t)(m + r) * D) + lane;
; #pragma unroll
;               for (int j = 0; j < 4; ++j) { u32x2 w; w.x = pk2(v[r][j][0], v[r][j][1]); w.y = pk2(v[r][j][2], v[r][j][3]); o[64 * j] = w; }
.Lxn_b_p:
	s_lshl_b32 s4, s0, 11
	s_add_u32 s4, s22, s4
	s_addc_u32 s5, s23, 0
	s_lshl_b32 s20, s0, 3
	s_add_u32 s20, s24, s20
	s_addc_u32 s21, s25, 0
	v_mul_f32_e32 v60, v24, v24
	v_fmac_f32_e32 v60, v25, v25
	v_mul_f32_e32 v61, v26, v26
	v_fmac_f32_e32 v61, v27, v27
	v_add_f32_e32 v60, v60, v61
	v_mov_b32_e32 v62, v60
	v_mul_f32_e32 v60, v28, v28
	v_fmac_f32_e32 v60, v29, v29
	v_mul_f32_e32 v61, v30, v30
	v_fmac_f32_e32 v61, v31, v31
	v_add_f32_e32 v60, v60, v61
	v_add_f32_e32 v62, v62, v60
	v_mul_f32_e32 v60, v32, v32
	v_fmac_f32_e32 v60, v33, v33
	v_mul_f32_e32 v61, v34, v34
	v_fmac_f32_e32 v61, v35, v35
	v_add_f32_e32 v60, v60, v61
	v_add_f32_e32 v62, v62, v60
	v_mul_f32_e32 v60, v36, v36
	v_fmac_f32_e32 v60, v37, v37
	v_mul_f32_e32 v61, v38, v38
	v_fmac_f32_e32 v61, v39, v39
	v_add_f32_e32 v60, v60, v61
	v_add_f32_e32 v62, v62, v60
	s_nop 1
	v_add_f32_dpp v62, v62, v62 quad_perm:[1,0,3,2] row_mask:0xf bank_mask:0xf
	s_nop 1
	v_add_f32_dpp v62, v62, v62 quad_perm:[2,3,0,1] row_mask:0xf bank_mask:0xf
	s_nop 1
	v_add_f32_dpp v62, v62, v62 row_half_mirror row_mask:0xf bank_mask:0xf
	s_nop 1
	v_add_f32_dpp v62, v62, v62 row_mirror row_mask:0xf bank_mask:0xf
	s_nop 1
	v_readlane_b32 s38, v62, 0
	v_readlane_b32 s39, v62, 16
	v_readlane_b32 s40, v62, 32
	v_readlane_b32 s41, v62, 48
	s_nop 2
	v_mov_b32_e32 v63, s38
	v_add_f32_e32 v63, s39, v63
	v_add_f32_e32 v63, s40, v63
	v_add_f32_e32 v63, s41, v63
	v_mul_f32_e32 v64, 0x53800000, v63
	v_trunc_f32_e32 v64, v64
	v_mul_f32_e32 v65, 0x2f800000, v64
	v_floor_f32_e32 v65, v65
	v_fmac_f32_e32 v64, 0xcf800000, v65
	v_cvt_u32_f32_e32 v64, v64
	v_cvt_u32_f32_e32 v65, v65
	s_mov_b64 exec, 1
	global_store_dwordx2 v1, v[64:65], s[20:21] sc1
	s_mov_b64 exec, -1
	v_cvt_pk_bf16_f32 v66, v24, v25
	v_cvt_pk_bf16_f32 v67, v26, v27
	global_store_dwordx2 v3, v[66:67], s[4:5] offset:0 sc1
	v_cvt_pk_bf16_f32 v68, v28, v29
	v_cvt_pk_bf16_f32 v69, v30, v31
	global_store_dwordx2 v3, v[68:69], s[4:5] offset:512 sc1
	v_cvt_pk_bf16_f32 v70, v32, v33
	v_cvt_pk_bf16_f32 v71, v34, v35
	global_store_dwordx2 v3, v[70:71], s[4:5] offset:1024 sc1
	v_cvt_pk_bf16_f32 v72, v36, v37
	v_cvt_pk_bf16_f32 v73, v38, v39
	global_store_dwordx2 v3, v[72:73], s[4:5] offset:1536 sc1
	s_add_u32 s0, s0, s1
	s_cmp_lt_u32 s0, 0x8000
	s_cbranch_scc0 .LBB0_98

; __device__ __forceinline__ u64 ss_fix(float s) { return (u64)(s * 1099511627776.0f); }
; __device__ __forceinline__ unsigned pk2(float lo, float hi) { return f2bf(lo) | (f2bf(hi) << 16); }
; __device__ __forceinline__ void prologue(const Args& a, LAS unsigned char* lds, int wave, int lane) {
;     ...
;           const f32x4* xr = (const f32x4*)(x + (size_t)m * D) + lane; f32x4 v[2][4]; float s[2] = {0.f, 0.f};
; #pragma unroll
;           for (int r = 0; r < 2; ++r)
; #pragma unroll
;               for (int j = 0; j < 4; ++j) v[r][j] = xr[r * (D / 4) + 64 * j];
; #pragma unroll
;           for (int r = 0; r < 2; ++r) {
; #pragma unroll
;               for (int j = 0; j < 4; ++j) s[r] += (v[r][j][0] * v[r][j][0] + v[r][j][1] * v[r][j][1]) + (v[r][j][2] * v[r][j][2] + v[r][j][3] * v[r][j][3]);
;               s[r] = wave_sum(s[r]); if (lane == 0) rs0[m + r] = ss_fix(s[r]);
;               u32x2* o = (u32x2*)(XN + (size_t)(m + r) * D) + lane;
; #pragma unroll
;               for (int j = 0; j < 4; ++j) { u32x2 w; w.x = pk2(v[r][j][0], v[r][j][1]); w.y = pk2(v[r][j][2], v[r][j][3]); o[64 * j] = w; }
.Lxn_c_p:
	s_lshl_b32 s4, s0, 11
	s_add_u32 s4, s22, s4
	s_addc_u32 s5, s23, 0
	s_lshl_b32 s20, s0, 3
	s_add_u32 s20, s24, s20
	s_addc_u32 s21, s25, 0
	v_mul_f32_e32 v60, v40, v40
	v_fmac_f32_e32 v60, v41, v41
	v_mul_f32_e32 v61, v42, v42
	v_fmac_f32_e32 v61, v43, v43
	v_add_f32_e32 v60, v60, v61
	v_mov_b32_e32 v62, v60
	v_mul_f32_e32 v60, v44, v44
	v_fmac_f32_e32 v60, v45, v45
	v_mul_f32_e32 v61, v46, v46
	v_fmac_f32_e32 v61, v47, v47
	v_add_f32_e32 v60, v60, v61
	v_add_f32_e32 v62, v62, v60
	v_mul_f32_e32 v60, v48, v48
	v_fmac_f32_e32 v60, v49, v49
	v_mul_f32_e32 v61, v50, v50
	v_fmac_f32_e32 v61, v51, v51
	v_add_f32_e32 v60, v60, v61
	v_add_f32_e32 v62, v62, v60
	v_mul_f32_e32 v60, v52, v52
	v_fmac_f32_e32 v60, v53, v53
	v_mul_f32_e32 v61, v54, v54
	v_fmac_f32_e32 v61, v55, v55
	v_add_f32_e32 v60, v60, v61
	v_add_f32_e32 v62, v62, v60
	s_nop 1
	v_add_f32_dpp v62, v62, v62 quad_perm:[1,0,3,2] row_mask:0xf bank_mask:0xf
	s_nop 1
	v_add_f32_dpp v62, v62, v62 quad_perm:[2,3,0,1] row_mask:0xf bank_mask:0xf
	s_nop 1
	v_add_f32_dpp v62, v62, v62 row_half_mirror row_mask:0xf bank_mask:0xf
	s_nop 1
	v_add_f32_dpp v62, v62, v62 row_mirror row_mask:0xf bank_mask:0xf
	s_nop 1
	v_readlane_b32 s38, v62, 0
	v_readlane_b32 s39, v62, 16
	v_readlane_b32 s40, v62, 32
	v_readlane_b32 s41, v62, 48
	s_nop 2
	v_mov_b32_e32 v63, s38
	v_add_f32_e32 v63, s39, v63
	v_add_f32_e32 v63, s40, v63
	v_add_f32_e32 v63, s41, v63
	v_mul_f32_e32 v64, 0x53800000, v63
	v_trunc_f32_e32 v64, v64
	v_mul_f32_e32 v65, 0x2f800000, v64
	v_floor_f32_e32 v65, v65
	v_fmac_f32_e32 v64, 0xcf800000, v65
	v_cvt_u32_f32_e32 v64, v64
	v_cvt_u32_f32_e32 v65, v65
	s_mov_b64 exec, 1
	global_store_dwordx2 v1, v[64:65], s[20:21] sc1
	s_mov_b64 exec, -1
	v_cvt_pk_bf16_f32 v66, v40, v41
	v_cvt_pk_bf16_f32 v67, v42, v43
	global_store_dwordx2 v3, v[66:67], s[4:5] offset:0 sc1
	v_cvt_pk_bf16_f32 v68, v44, v45
	v_cvt_pk_bf16_f32 v69, v46, v47
	global_store_dwordx2 v3, v[68:69], s[4:5] offset:512 sc1
	v_cvt_pk_bf16_f32 v70, v48, v49
	v_cvt_pk_bf16_f32 v71, v50, v51
	global_store_dwordx2 v3, v[70:71], s[4:5] offset:1024 sc1
	v_cvt_pk_bf16_f32 v72, v52, v53
	v_cvt_pk_bf16_f32 v73, v54, v55
	global_store_dwordx2 v3, v[72:73], s[4:5] offset:1536 sc1
	s_add_u32 s0, s0, s1
	s_cmp_lt_u32 s0, 0x8000
	s_cbranch_scc0 .LBB0_98

; __device__ __forceinline__ u64 ss_fix(float s) { return (u64)(s * 1099511627776.0f); }
; __device__ __forceinline__ unsigned pk2(float lo, float hi) { return f2bf(lo) | (f2bf(hi) << 16); }
; __device__ __forceinline__ void prologue(const Args& a, LAS unsigned char* lds, int wave, int lane) {
;     ...
;           const f32x4* xr = (const f32x4*)(x + (size_t)m * D) + lane; f32x4 v[2][4]; float s[2] = {0.f, 0.f};
; #pragma unroll
;           for (int r = 0; r < 2; ++r)
; #pragma unroll
;               for (int j = 0; j < 4; ++j) v[r][j] = xr[r * (D / 4) + 64 * j];
; #pragma unroll
;           for (int r = 0; r < 2; ++r) {
; #pragma unroll
;               for (int j = 0; j < 4; ++j) s[r] += (v[r][j][0] * v[r][j][0] + v[r][j][1] * v[r][j][1]) + (v[r][j][2] * v[r][j][2] + v[r][j][3] * v[r][j][3]);
;               s[r] = wave_sum(s[r]); if (lane == 0) rs0[m + r] = ss_fix(s[r]);
;               u32x2* o = (u32x2*)(XN + (size_t)(m + r) * D) + lane;
; #pragma unroll
;               for (int j = 0; j < 4; ++j) { u32x2 w; w.x = pk2(v[r][j][0], v[r][j][1]); w.y = pk2(v[r][j][2], v[r][j][3]); o[64 * j] = w; }
.Lxn_e_p:
	s_lshl_b32 s4, s0, 11
	s_add_u32 s4, s22, s4
	s_addc_u32 s5, s23, 0
	s_lshl_b32 s20, s0, 3
	s_add_u32 s20, s24, s20
	s_addc_u32 s21, s25, 0
	v_mul_f32_e32 v60, v24, v24
	v_fmac_f32_e32 v60, v25, v25
	v_mul_f32_e32 v61, v26, v26
	v_fmac_f32_e32 v61, v27, v27
	v_add_f32_e32 v60, v60, v61
	v_mov_b32_e32 v62, v60
	v_mul_f32_e32 v60, v28, v28
	v_fmac_f32_e32 v60, v29, v29
	v_mul_f32_e32 v61, v30, v30
	v_fmac_f32_e32 v61, v31, v31
	v_add_f32_e32 v60, v60, v61
	v_add_f32_e32 v62, v62, v60
	v_mul_f32_e32 v60, v32, v32
	v_fmac_f32_e32 v60, v33, v33
	v_mul_f32_e32 v61, v34, v34
	v_fmac_f32_e32 v61, v35, v35
	v_add_f32_e32 v60, v60, v61
	v_add_f32_e32 v62, v62, v60
	v_mul_f32_e32 v60, v36, v36
	v_fmac_f32_e32 v60, v37, v37
	v_mul_f32_e32 v61, v38, v38
	v_fmac_f32_e32 v61, v39, v39
	v_add_f32_e32 v60, v60, v61
	v_add_f32_e32 v62, v62, v60
	s_nop 1
	v_add_f32_dpp v62, v62, v62 quad_perm:[1,0,3,2] row_mask:0xf bank_mask:0xf
	s_nop 1
	v_add_f32_dpp v62, v62, v62 quad_perm:[2,3,0,1] row_mask:0xf bank_mask:0xf
	s_nop 1
	v_add_f32_dpp v62, v62, v62 row_half_mirror row_mask:0xf bank_mask:0xf
	s_nop 1
	v_add_f32_dpp v62, v62, v62 row_mirror row_mask:0xf bank_mask:0xf
	s_nop 1
	v_readlane_b32 s38, v62, 0
	v_readlane_b32 s39, v62, 16
	v_readlane_b32 s40, v62, 32
	v_readlane_b32 s41, v62, 48
	s_nop 2
	v_mov_b32_e32 v63, s38
	v_add_f32_e32 v63, s39, v63
	v_add_f32_e32 v63, s40, v63
	v_add_f32_e32 v63, s41, v63
	v_mul_f32_e32 v64, 0x53800000, v63
	v_trunc_f32_e32 v64, v64
	v_mul_f32_e32 v65, 0x2f800000, v64
	v_floor_f32_e32 v65, v65
	v_fmac_f32_e32 v64, 0xcf800000, v65
	v_cvt_u32_f32_e32 v64, v64
	v_cvt_u32_f32_e32 v65, v65
	s_mov_b64 exec, 1
	global_store_dwordx2 v1, v[64:65], s[20:21] sc1
	s_mov_b64 exec, -1
	v_cvt_pk_bf16_f32 v66, v24, v25
	v_cvt_pk_bf16_f32 v67, v26, v27
	global_store_dwordx2 v3, v[66:67], s[4:5] offset:0 sc1
	v_cvt_pk_bf16_f32 v68, v28, v29
	v_cvt_pk_bf16_f32 v69, v30, v31
	global_store_dwordx2 v3, v[68:69], s[4:5] offset:512 sc1
	v_cvt_pk_bf16_f32 v70, v32, v33
	v_cvt_pk_bf16_f32 v71, v34, v35
	global_store_dwordx2 v3, v[70:71], s[4:5] offset:1024 sc1
	v_cvt_pk_bf16_f32 v72, v36, v37
	v_cvt_pk_bf16_f32 v73, v38, v39
	global_store_dwordx2 v3, v[72:73], s[4:5] offset:1536 sc1
	s_add_u32 s0, s0, s1
	s_cmp_lt_u32 s0, 0x8000
	s_cbranch_scc0 .LBB0_98
	s_branch .Lxn_c

; __device__ __forceinline__ unsigned pk2(float lo, float hi) { return f2bf(lo) | (f2bf(hi) << 16); }
; __device__ __forceinline__ void gla_scan(const float* UPD, const float* DEC, bf16* ST, int gtid, int gthreads) {
;     ...
;         for (int c0 = 0; c0 < 64; c0 += 16) {
;             f32x4 dv[16], uv[16];
; #pragma unroll
;             for (int i = 0; i < 16; ++i) { const size_t unit = (size_t)((c0 + i) * 4 + h); dv[i] = *(const f32x4*)(DEC + unit * 64 + 4 * kq); uv[i] = *(const f32x4*)(UPD + unit * 8192 + v * 64 + 4 * kq); }
;             asm volatile("" : "+v"(dv[0]), "+v"(dv[1]), "+v"(dv[2]), "+v"(dv[3]), "+v"(dv[4]), "+v"(dv[5]), "+v"(dv[6]), "+v"(dv[7]) :: "memory");
;             asm volatile("" : "+v"(dv[8]), "+v"(dv[9]), "+v"(dv[10]), "+v"(dv[11]), "+v"(dv[12]), "+v"(dv[13]), "+v"(dv[14]), "+v"(dv[15]) :: "memory");
;             asm volatile("" : "+v"(uv[0]), "+v"(uv[1]), "+v"(uv[2]), "+v"(uv[3]), "+v"(uv[4]), "+v"(uv[5]), "+v"(uv[6]), "+v"(uv[7]) :: "memory");
;             asm volatile("" : "+v"(uv[8]), "+v"(uv[9]), "+v"(uv[10]), "+v"(uv[11]), "+v"(uv[12]), "+v"(uv[13]), "+v"(uv[14]), "+v"(uv[15]) :: "memory");
; #pragma unroll
;             for (int i = 0; i < 16; ++i) {
;                 const size_t unit = (size_t)((c0 + i) * 4 + h);
;                 s = dv[i] * s + uv[i];
;                 u32x2 w; w.x = pk2(s[0], s[1]); w.y = pk2(s[2], s[3]);
;                 *(u32x2*)(ST + unit * 8192 + v * 64 + 4 * kq) = w;
.LBB0_473:
	v_lshl_add_u64 v[26:27], s[34:35], 0, v[18:19]
	v_add_co_u32_e32 v0, vcc, 0x401000, v26
	v_lshl_add_u64 v[24:25], s[34:35], 0, v[16:17]
	s_nop 0
	v_addc_co_u32_e32 v1, vcc, 0, v27, vcc
	v_add_co_u32_e32 v2, vcc, 0x400000, v26
	global_load_dwordx4 v[48:51], v[0:1], off offset:3072
	global_load_dwordx4 v[52:55], v[0:1], off offset:2048
	global_load_dwordx4 v[56:59], v[0:1], off offset:1024
	global_load_dwordx4 v[60:63], v[0:1], off
	v_addc_co_u32_e32 v3, vcc, 0, v27, vcc
	v_add_co_u32_e32 v80, vcc, 0x403000, v26
	global_load_dwordx4 v[64:67], v[2:3], off offset:3072
	global_load_dwordx4 v[68:71], v[2:3], off offset:2048
	global_load_dwordx4 v[72:75], v[2:3], off offset:1024
	global_load_dwordx4 v[76:79], v[2:3], off
	v_addc_co_u32_e32 v81, vcc, 0, v27, vcc
	v_add_co_u32_e32 v26, vcc, 0x402000, v26
	global_load_dwordx4 v[0:3], v[80:81], off offset:3072
	global_load_dwordx4 v[4:7], v[80:81], off offset:2048
	global_load_dwordx4 v[8:11], v[80:81], off offset:1024
	s_nop 0
	global_load_dwordx4 v[80:83], v[80:81], off
	v_addc_co_u32_e32 v27, vcc, 0, v27, vcc
	v_add_co_u32_e32 v100, vcc, 0x190e0000, v24
	global_load_dwordx4 v[84:87], v[26:27], off offset:3072
	global_load_dwordx4 v[88:91], v[26:27], off offset:2048
	global_load_dwordx4 v[92:95], v[26:27], off offset:1024
	global_load_dwordx4 v[96:99], v[26:27], off
	v_addc_co_u32_e32 v101, vcc, 0, v25, vcc
	v_add_co_u32_e32 v26, vcc, 0x190c0000, v24
	v_lshl_add_u64 v[28:29], s[34:35], 0, v[14:15]
	s_nop 0
	v_addc_co_u32_e32 v27, vcc, 0, v25, vcc
	v_add_co_u32_e32 v108, vcc, 0x190a0000, v24
	global_load_dwordx4 v[100:103], v[100:101], off
	s_nop 0
	global_load_dwordx4 v[104:107], v[26:27], off
	v_addc_co_u32_e32 v109, vcc, 0, v25, vcc
	v_add_co_u32_e32 v26, vcc, 0x19080000, v24
	v_add_co_u32_e64 v160, s[0:1], s21, v28
	s_nop 0
	v_addc_co_u32_e32 v27, vcc, 0, v25, vcc
	v_add_co_u32_e32 v116, vcc, 0x19060000, v24
	global_load_dwordx4 v[108:111], v[108:109], off
	s_nop 0
	global_load_dwordx4 v[112:115], v[26:27], off
	v_addc_co_u32_e32 v117, vcc, 0, v25, vcc
	v_add_co_u32_e32 v26, vcc, 0x19040000, v24
	v_addc_co_u32_e64 v161, s[0:1], 0, v29, s[0:1]
	s_nop 0
	v_addc_co_u32_e32 v27, vcc, 0, v25, vcc
	v_add_co_u32_e32 v124, vcc, 0x19020000, v24
	global_load_dwordx4 v[116:119], v[116:117], off
	s_nop 0
	global_load_dwordx4 v[120:123], v[26:27], off
	v_addc_co_u32_e32 v125, vcc, 0, v25, vcc
	v_add_co_u32_e32 v26, vcc, 0x19000000, v24
	v_add_co_u32_e64 v162, s[0:1], s28, v28
	s_nop 0
	v_addc_co_u32_e32 v27, vcc, 0, v25, vcc
	v_add_co_u32_e32 v132, vcc, 0x191e0000, v24
	global_load_dwordx4 v[124:127], v[124:125], off
	s_nop 0
	global_load_dwordx4 v[128:131], v[26:27], off
	v_addc_co_u32_e32 v133, vcc, 0, v25, vcc
	v_add_co_u32_e32 v26, vcc, 0x191c0000, v24
	v_addc_co_u32_e64 v163, s[0:1], 0, v29, s[0:1]
	s_nop 0
	v_addc_co_u32_e32 v27, vcc, 0, v25, vcc
	v_add_co_u32_e32 v140, vcc, 0x191a0000, v24
	global_load_dwordx4 v[132:135], v[132:133], off
	s_nop 0
	global_load_dwordx4 v[136:139], v[26:27], off
	v_addc_co_u32_e32 v141, vcc, 0, v25, vcc
	v_add_co_u32_e32 v26, vcc, 0x19180000, v24
	v_add_co_u32_e64 v164, s[0:1], s29, v28
	s_nop 0
	v_addc_co_u32_e32 v27, vcc, 0, v25, vcc
	v_add_co_u32_e32 v148, vcc, 0x19160000, v24
	global_load_dwordx4 v[140:143], v[140:141], off
	s_nop 0
	global_load_dwordx4 v[144:147], v[26:27], off
	v_addc_co_u32_e32 v149, vcc, 0, v25, vcc
	v_add_co_u32_e32 v26, vcc, 0x19140000, v24
	v_addc_co_u32_e64 v165, s[0:1], 0, v29, s[0:1]
	s_nop 0
	v_addc_co_u32_e32 v27, vcc, 0, v25, vcc
	v_add_co_u32_e32 v156, vcc, 0x19120000, v24
	global_load_dwordx4 v[148:151], v[148:149], off
	s_nop 0
	global_load_dwordx4 v[152:155], v[26:27], off
	v_addc_co_u32_e32 v157, vcc, 0, v25, vcc
	v_add_co_u32_e32 v158, vcc, 0x19100000, v24
	v_add_co_u32_e64 v166, s[0:1], s30, v28
	s_nop 0
	v_addc_co_u32_e32 v159, vcc, 0, v25, vcc
	global_load_dwordx4 v[24:27], v[156:157], off
	s_nop 0
	global_load_dwordx4 v[156:159], v[158:159], off
	v_addc_co_u32_e64 v167, s[0:1], 0, v29, s[0:1]
	v_add_co_u32_e64 v168, s[0:1], s31, v28
	s_waitcnt vmcnt(24)
	s_waitcnt vmcnt(16)
	s_waitcnt vmcnt(8)
	v_addc_co_u32_e64 v169, s[0:1], 0, v29, s[0:1]
	v_add_co_u32_e64 v170, s[0:1], s37, v28
	v_pk_fma_f32 v[22:23], v[22:23], v[78:79], v[130:131]
	s_nop 0
	v_addc_co_u32_e64 v171, s[0:1], 0, v29, s[0:1]
	v_pk_fma_f32 v[20:21], v[20:21], v[76:77], v[128:129]
	v_add_co_u32_e64 v172, s[0:1], s39, v28
	v_bfe_u32 v12, v20, 16, 1
	v_bfe_u32 v76, v21, 16, 1
	v_bfe_u32 v77, v22, 16, 1
	v_bfe_u32 v78, v23, 16, 1
	v_pk_fma_f32 v[74:75], v[74:75], v[22:23], v[126:127]
	v_pk_fma_f32 v[72:73], v[72:73], v[20:21], v[124:125]
	v_addc_co_u32_e64 v173, s[0:1], 0, v29, s[0:1]
	v_add3_u32 v12, v20, v12, s11
	v_add3_u32 v76, v21, v76, s11
	v_add3_u32 v77, v22, v77, s11
	v_add3_u32 v78, v23, v78, s11
	v_bfe_u32 v79, v72, 16, 1
	v_bfe_u32 v124, v73, 16, 1
	v_bfe_u32 v125, v74, 16, 1
	v_bfe_u32 v126, v75, 16, 1
	v_pk_fma_f32 v[20:21], v[70:71], v[74:75], v[122:123]
	v_pk_fma_f32 v[22:23], v[68:69], v[72:73], v[120:121]
	v_add_co_u32_e64 v44, s[0:1], s56, v28
	v_lshrrev_b32_e32 v12, 16, v12
	v_lshrrev_b32_e32 v69, 16, v77
	v_add3_u32 v70, v72, v79, s11
	v_add3_u32 v71, v73, v124, s11
	v_add3_u32 v72, v74, v125, s11
	v_add3_u32 v73, v75, v126, s11
	v_bfe_u32 v74, v22, 16, 1
	v_bfe_u32 v75, v23, 16, 1
	v_bfe_u32 v77, v20, 16, 1
	v_bfe_u32 v79, v21, 16, 1
	v_pk_fma_f32 v[66:67], v[66:67], v[20:21], v[118:119]
	v_pk_fma_f32 v[64:65], v[64:65], v[22:23], v[116:117]
	v_addc_co_u32_e64 v45, s[0:1], 0, v29, s[0:1]
	v_and_or_b32 v68, v76, s20, v12
	v_and_or_b32 v69, v78, s20, v69
	v_lshrrev_b32_e32 v12, 16, v70
	v_lshrrev_b32_e32 v70, 16, v72
	v_add3_u32 v72, v22, v74, s11
	v_add3_u32 v74, v23, v75, s11
	v_add3_u32 v75, v20, v77, s11
	v_add3_u32 v76, v21, v79, s11
	v_bfe_u32 v77, v64, 16, 1
	v_bfe_u32 v78, v65, 16, 1
	v_bfe_u32 v79, v66, 16, 1
	v_bfe_u32 v116, v67, 16, 1
	v_pk_fma_f32 v[20:21], v[62:63], v[66:67], v[114:115]
	v_pk_fma_f32 v[22:23], v[60:61], v[64:65], v[112:113]
	v_add_co_u32_e64 v42, s[0:1], s57, v28
	s_waitcnt vmcnt(0)
; __device__ __forceinline__ unsigned pk2(float lo, float hi) { return f2bf(lo) | (f2bf(hi) << 16); }
; __device__ __forceinline__ void gla_scan(const float* UPD, const float* DEC, bf16* ST, int gtid, int gthreads) {
;     ...
;             for (int i = 0; i < 16; ++i) {
;                 const size_t unit = (size_t)((c0 + i) * 4 + h);
;                 s = dv[i] * s + uv[i];
;                 u32x2 w; w.x = pk2(s[0], s[1]); w.y = pk2(s[2], s[3]);
;                 *(u32x2*)(ST + unit * 8192 + v * 64 + 4 * kq) = w;
	global_store_dwordx2 v[160:161], v[68:69], off sc1
	v_and_or_b32 v60, v71, s20, v12
	v_and_or_b32 v61, v73, s20, v70
	v_lshrrev_b32_e32 v12, 16, v72
	v_lshrrev_b32_e32 v62, 16, v75
	v_add3_u32 v63, v64, v77, s11
	v_add3_u32 v64, v65, v78, s11
	v_add3_u32 v65, v66, v79, s11
	v_add3_u32 v66, v67, v116, s11
	v_bfe_u32 v67, v22, 16, 1
	v_bfe_u32 v68, v23, 16, 1
	v_bfe_u32 v69, v20, 16, 1
	v_bfe_u32 v70, v21, 16, 1
	v_pk_fma_f32 v[58:59], v[58:59], v[20:21], v[110:111]
	v_pk_fma_f32 v[56:57], v[56:57], v[22:23], v[108:109]
	v_addc_co_u32_e64 v43, s[0:1], 0, v29, s[0:1]
	global_store_dwordx2 v[162:163], v[60:61], off sc1
	v_and_or_b32 v60, v74, s20, v12
	v_and_or_b32 v61, v76, s20, v62
	v_lshrrev_b32_e32 v12, 16, v63
	v_lshrrev_b32_e32 v62, 16, v65
	v_add3_u32 v63, v22, v67, s11
	v_add3_u32 v65, v23, v68, s11
	v_add3_u32 v67, v20, v69, s11
	v_add3_u32 v68, v21, v70, s11
	v_bfe_u32 v69, v56, 16, 1
	v_bfe_u32 v70, v57, 16, 1
	v_bfe_u32 v71, v58, 16, 1
	v_bfe_u32 v72, v59, 16, 1
	v_pk_fma_f32 v[20:21], v[54:55], v[58:59], v[106:107]
	v_pk_fma_f32 v[22:23], v[52:53], v[56:57], v[104:105]
	v_add_co_u32_e64 v40, s[0:1], s70, v28
	global_store_dwordx2 v[164:165], v[60:61], off sc1
	v_and_or_b32 v52, v64, s20, v12
	v_and_or_b32 v53, v66, s20, v62
	v_lshrrev_b32_e32 v12, 16, v63
	v_lshrrev_b32_e32 v54, 16, v67
	v_add3_u32 v55, v56, v69, s11
	v_add3_u32 v56, v57, v70, s11
	v_add3_u32 v57, v58, v71, s11
	v_add3_u32 v58, v59, v72, s11
	v_bfe_u32 v59, v22, 16, 1
	v_bfe_u32 v60, v23, 16, 1
	v_bfe_u32 v61, v20, 16, 1
	v_bfe_u32 v62, v21, 16, 1
	v_pk_fma_f32 v[50:51], v[50:51], v[20:21], v[102:103]
	v_pk_fma_f32 v[48:49], v[48:49], v[22:23], v[100:101]
	v_addc_co_u32_e64 v41, s[0:1], 0, v29, s[0:1]
	global_store_dwordx2 v[166:167], v[52:53], off sc1
	v_and_or_b32 v52, v65, s20, v12
	v_and_or_b32 v53, v68, s20, v54
	v_lshrrev_b32_e32 v12, 16, v55
	v_lshrrev_b32_e32 v54, 16, v57
	v_add3_u32 v55, v22, v59, s11
	v_add3_u32 v57, v23, v60, s11
	v_add3_u32 v59, v20, v61, s11
	v_add3_u32 v60, v21, v62, s11
	v_bfe_u32 v61, v48, 16, 1
	v_bfe_u32 v62, v49, 16, 1
	v_bfe_u32 v63, v50, 16, 1
	v_pk_fma_f32 v[20:21], v[98:99], v[50:51], v[158:159]
	v_pk_fma_f32 v[22:23], v[96:97], v[48:49], v[156:157]
	v_add_co_u32_e64 v38, s[0:1], s71, v28
	v_bfe_u32 v64, v51, 16, 1
	global_store_dwordx2 v[168:169], v[52:53], off sc1
	v_and_or_b32 v52, v56, s20, v12
	v_and_or_b32 v53, v58, s20, v54
	v_lshrrev_b32_e32 v12, 16, v55
	v_lshrrev_b32_e32 v54, 16, v59
	v_add3_u32 v55, v48, v61, s11
	v_add3_u32 v56, v49, v62, s11
	v_add3_u32 v50, v50, v63, s11
	v_bfe_u32 v58, v22, 16, 1
	v_bfe_u32 v59, v23, 16, 1
	v_bfe_u32 v61, v20, 16, 1
	v_bfe_u32 v62, v21, 16, 1
	v_pk_fma_f32 v[26:27], v[94:95], v[20:21], v[26:27]
	v_pk_fma_f32 v[24:25], v[92:93], v[22:23], v[24:25]
	v_addc_co_u32_e64 v39, s[0:1], 0, v29, s[0:1]
	v_add3_u32 v51, v51, v64, s11
	global_store_dwordx2 v[170:171], v[52:53], off sc1
	v_and_or_b32 v48, v57, s20, v12
	v_and_or_b32 v49, v60, s20, v54
	v_lshrrev_b32_e32 v12, 16, v55
	v_lshrrev_b32_e32 v50, 16, v50
	v_add3_u32 v52, v22, v58, s11
	v_add3_u32 v53, v23, v59, s11
	v_add3_u32 v54, v20, v61, s11
	v_add3_u32 v55, v21, v62, s11
	v_bfe_u32 v57, v24, 16, 1
	v_bfe_u32 v58, v25, 16, 1
	v_bfe_u32 v59, v26, 16, 1
	v_bfe_u32 v60, v27, 16, 1
	v_pk_fma_f32 v[20:21], v[90:91], v[26:27], v[154:155]
	v_pk_fma_f32 v[22:23], v[88:89], v[24:25], v[152:153]
	v_add_co_u32_e64 v36, s[0:1], s72, v28
	global_store_dwordx2 v[172:173], v[48:49], off sc1
	v_and_or_b32 v48, v56, s20, v12
	v_and_or_b32 v49, v51, s20, v50
	v_lshrrev_b32_e32 v12, 16, v52
	v_lshrrev_b32_e32 v50, 16, v54
	v_add3_u32 v51, v24, v57, s11
	v_add3_u32 v52, v25, v58, s11
	v_add3_u32 v54, v26, v59, s11
	v_add3_u32 v56, v27, v60, s11
	v_bfe_u32 v57, v22, 16, 1
	v_bfe_u32 v58, v23, 16, 1
	v_bfe_u32 v59, v20, 16, 1
	v_bfe_u32 v60, v21, 16, 1
	v_pk_fma_f32 v[24:25], v[86:87], v[20:21], v[150:151]
; __device__ __forceinline__ unsigned pk2(float lo, float hi) { return f2bf(lo) | (f2bf(hi) << 16); }
; __device__ __forceinline__ void gla_scan(const float* UPD, const float* DEC, bf16* ST, int gtid, int gthreads) {
;     for (int p = gtid; p < 4 * 128 * 16; p += gthreads) {
;         const int h = p >> 11, rem = p & 2047, v = rem >> 4, kq = rem & 15;
;         f32x4 s = (f32x4){0.f, 0.f, 0.f, 0.f};
; #pragma unroll 1
;         for (int c0 = 0; c0 < 64; c0 += 16) {
;             f32x4 dv[16], uv[16];
; #pragma unroll
;             for (int i = 0; i < 16; ++i) { const size_t unit = (size_t)((c0 + i) * 4 + h); dv[i] = *(const f32x4*)(DEC + unit * 64 + 4 * kq); uv[i] = *(const f32x4*)(UPD + unit * 8192 + v * 64 + 4 * kq); }
;             asm volatile("" : "+v"(dv[0]), "+v"(dv[1]), "+v"(dv[2]), "+v"(dv[3]), "+v"(dv[4]), "+v"(dv[5]), "+v"(dv[6]), "+v"(dv[7]) :: "memory");
;             asm volatile("" : "+v"(dv[8]), "+v"(dv[9]), "+v"(dv[10]), "+v"(dv[11]), "+v"(dv[12]), "+v"(dv[13]), "+v"(dv[14]), "+v"(dv[15]) :: "memory");
;             asm volatile("" : "+v"(uv[0]), "+v"(uv[1]), "+v"(uv[2]), "+v"(uv[3]), "+v"(uv[4]), "+v"(uv[5]), "+v"(uv[6]), "+v"(uv[7]) :: "memory");
;             asm volatile("" : "+v"(uv[8]), "+v"(uv[9]), "+v"(uv[10]), "+v"(uv[11]), "+v"(uv[12]), "+v"(uv[13]), "+v"(uv[14]), "+v"(uv[15]) :: "memory");
; #pragma unroll
;             for (int i = 0; i < 16; ++i) {
;                 const size_t unit = (size_t)((c0 + i) * 4 + h);
;                 s = dv[i] * s + uv[i];
;                 u32x2 w; w.x = pk2(s[0], s[1]); w.y = pk2(s[2], s[3]);
;                 *(u32x2*)(ST + unit * 8192 + v * 64 + 4 * kq) = w;
;             }
	v_pk_fma_f32 v[26:27], v[84:85], v[22:23], v[148:149]
	v_addc_co_u32_e64 v37, s[0:1], 0, v29, s[0:1]
	global_store_dwordx2 v[44:45], v[48:49], off sc1
	v_and_or_b32 v44, v53, s20, v12
	v_and_or_b32 v45, v55, s20, v50
	v_lshrrev_b32_e32 v12, 16, v51
	v_lshrrev_b32_e32 v48, 16, v54
	v_add3_u32 v49, v22, v57, s11
	v_add3_u32 v50, v23, v58, s11
	v_add3_u32 v51, v20, v59, s11
	v_add3_u32 v53, v21, v60, s11
	v_bfe_u32 v54, v26, 16, 1
	v_bfe_u32 v57, v24, 16, 1
	v_pk_fma_f32 v[20:21], v[82:83], v[24:25], v[146:147]
	v_pk_fma_f32 v[22:23], v[80:81], v[26:27], v[144:145]
	v_add_co_u32_e64 v34, s[0:1], s73, v28
	v_bfe_u32 v55, v27, 16, 1
	v_bfe_u32 v58, v25, 16, 1
	global_store_dwordx2 v[42:43], v[44:45], off sc1
	v_and_or_b32 v42, v52, s20, v12
	v_and_or_b32 v43, v56, s20, v48
	v_lshrrev_b32_e32 v12, 16, v49
	v_lshrrev_b32_e32 v44, 16, v51
	v_add3_u32 v26, v26, v54, s11
	v_add3_u32 v45, v24, v57, s11
	v_bfe_u32 v49, v22, 16, 1
	v_bfe_u32 v51, v23, 16, 1
	v_bfe_u32 v52, v20, 16, 1
	v_bfe_u32 v54, v21, 16, 1
	v_pk_fma_f32 v[10:11], v[10:11], v[20:21], v[142:143]
	v_pk_fma_f32 v[8:9], v[8:9], v[22:23], v[140:141]
	v_addc_co_u32_e64 v35, s[0:1], 0, v29, s[0:1]
	v_add3_u32 v27, v27, v55, s11
	v_add3_u32 v48, v25, v58, s11
	global_store_dwordx2 v[40:41], v[42:43], off sc1
	v_and_or_b32 v24, v50, s20, v12
	v_and_or_b32 v25, v53, s20, v44
	v_lshrrev_b32_e32 v12, 16, v26
	v_lshrrev_b32_e32 v26, 16, v45
	v_add3_u32 v22, v22, v49, s11
	v_add3_u32 v40, v23, v51, s11
	v_add3_u32 v20, v20, v52, s11
	v_add3_u32 v41, v21, v54, s11
	v_bfe_u32 v21, v8, 16, 1
	v_bfe_u32 v23, v9, 16, 1
	v_bfe_u32 v42, v10, 16, 1
	v_pk_fma_f32 v[6:7], v[6:7], v[10:11], v[138:139]
	v_pk_fma_f32 v[4:5], v[4:5], v[8:9], v[136:137]
	v_add_co_u32_e64 v32, s[0:1], s74, v28
	v_bfe_u32 v43, v11, 16, 1
	global_store_dwordx2 v[38:39], v[24:25], off sc1
	v_and_or_b32 v24, v27, s20, v12
	v_and_or_b32 v25, v48, s20, v26
	v_lshrrev_b32_e32 v12, 16, v22
	v_lshrrev_b32_e32 v26, 16, v20
	v_add3_u32 v8, v8, v21, s11
	v_add3_u32 v9, v9, v23, s11
	v_add3_u32 v10, v10, v42, s11
	v_bfe_u32 v27, v4, 16, 1
	v_bfe_u32 v39, v6, 16, 1
	v_pk_fma_f32 v[22:23], v[2:3], v[6:7], v[134:135]
	v_pk_fma_f32 v[20:21], v[0:1], v[4:5], v[132:133]
	v_addc_co_u32_e64 v33, s[0:1], 0, v29, s[0:1]
	v_add3_u32 v11, v11, v43, s11
	v_bfe_u32 v38, v5, 16, 1
	v_bfe_u32 v42, v7, 16, 1
	v_and_or_b32 v0, v40, s20, v12
	v_and_or_b32 v1, v41, s20, v26
	v_lshrrev_b32_e32 v2, 16, v8
	v_lshrrev_b32_e32 v3, 16, v10
	v_add3_u32 v4, v4, v27, s11
	v_add3_u32 v6, v6, v39, s11
	v_bfe_u32 v8, v20, 16, 1
	v_bfe_u32 v12, v22, 16, 1
	v_add_co_u32_e64 v30, s[0:1], s75, v28
	global_store_dwordx2 v[36:37], v[24:25], off sc1
	v_add3_u32 v5, v5, v38, s11
	v_add3_u32 v7, v7, v42, s11
	v_bfe_u32 v10, v21, 16, 1
	v_bfe_u32 v24, v23, 16, 1
	global_store_dwordx2 v[34:35], v[0:1], off sc1
	v_and_or_b32 v0, v9, s20, v2
	v_and_or_b32 v1, v11, s20, v3
	v_lshrrev_b32_e32 v2, 16, v4
	v_lshrrev_b32_e32 v3, 16, v6
	v_add3_u32 v4, v20, v8, s11
	v_add3_u32 v8, v22, v12, s11
	s_add_i32 s77, s77, 16
	v_addc_co_u32_e64 v31, s[0:1], 0, v29, s[0:1]
	v_add_co_u32_e32 v28, vcc, 0x1d0f0000, v28
	v_add3_u32 v6, v21, v10, s11
	v_add3_u32 v9, v23, v24, s11
	global_store_dwordx2 v[32:33], v[0:1], off sc1
	v_and_or_b32 v0, v5, s20, v2
	v_and_or_b32 v1, v7, s20, v3
	v_lshrrev_b32_e32 v2, 16, v4
	v_lshrrev_b32_e32 v3, 16, v8
	v_lshl_add_u64 v[14:15], v[14:15], 0, s[64:65]
	v_lshl_add_u64 v[16:17], v[16:17], 0, s[66:67]
	v_lshl_add_u64 v[18:19], v[18:19], 0, s[68:69]
	s_cmp_gt_u32 s77, 47
	v_addc_co_u32_e32 v29, vcc, 0, v29, vcc
	global_store_dwordx2 v[30:31], v[0:1], off sc1
	v_and_or_b32 v0, v6, s20, v2
	v_and_or_b32 v1, v9, s20, v3
	global_store_dwordx2 v[28:29], v[0:1], off sc1
	s_cbranch_scc0 .LBB0_473
	v_add_u32_e32 v46, s2, v46
	v_cmp_lt_i32_e32 vcc, s76, v46
	s_or_b64 s[62:63], vcc, s[62:63]
	v_add_u32_e32 v47, s3, v47
	s_andn2_b64 exec, exec, s[62:63]
	s_cbranch_execnz .LBB0_472

; __device__ __forceinline__ unsigned pk2(float lo, float hi) { return f2bf(lo) | (f2bf(hi) << 16); }
; __device__ __forceinline__ void gla_scan(const float* UPD, const float* DEC, bf16* ST, int gtid, int gthreads) {
;     ...
;         for (int c0 = 0; c0 < 64; c0 += 16) {
;             f32x4 dv[16], uv[16];
; #pragma unroll
;             for (int i = 0; i < 16; ++i) { const size_t unit = (size_t)((c0 + i) * 4 + h); dv[i] = *(const f32x4*)(DEC + unit * 64 + 4 * kq); uv[i] = *(const f32x4*)(UPD + unit * 8192 + v * 64 + 4 * kq); }
;             asm volatile("" : "+v"(dv[0]), "+v"(dv[1]), "+v"(dv[2]), "+v"(dv[3]), "+v"(dv[4]), "+v"(dv[5]), "+v"(dv[6]), "+v"(dv[7]) :: "memory");
;             asm volatile("" : "+v"(dv[8]), "+v"(dv[9]), "+v"(dv[10]), "+v"(dv[11]), "+v"(dv[12]), "+v"(dv[13]), "+v"(dv[14]), "+v"(dv[15]) :: "memory");
;             asm volatile("" : "+v"(uv[0]), "+v"(uv[1]), "+v"(uv[2]), "+v"(uv[3]), "+v"(uv[4]), "+v"(uv[5]), "+v"(uv[6]), "+v"(uv[7]) :: "memory");
;             asm volatile("" : "+v"(uv[8]), "+v"(uv[9]), "+v"(uv[10]), "+v"(uv[11]), "+v"(uv[12]), "+v"(uv[13]), "+v"(uv[14]), "+v"(uv[15]) :: "memory");
; #pragma unroll
;             for (int i = 0; i < 16; ++i) {
;                 const size_t unit = (size_t)((c0 + i) * 4 + h);
;                 s = dv[i] * s + uv[i];
;                 u32x2 w; w.x = pk2(s[0], s[1]); w.y = pk2(s[2], s[3]);
;                 *(u32x2*)(ST + unit * 8192 + v * 64 + 4 * kq) = w;
.LBB0_1106:
	v_lshl_add_u64 v[26:27], s[34:35], 0, v[18:19]
	v_add_co_u32_e32 v0, vcc, 0x401000, v26
	v_lshl_add_u64 v[24:25], s[34:35], 0, v[16:17]
	s_nop 0
	v_addc_co_u32_e32 v1, vcc, 0, v27, vcc
	v_add_co_u32_e32 v2, vcc, 0x400000, v26
	global_load_dwordx4 v[48:51], v[0:1], off offset:3072
	global_load_dwordx4 v[52:55], v[0:1], off offset:2048
	global_load_dwordx4 v[56:59], v[0:1], off offset:1024
	global_load_dwordx4 v[60:63], v[0:1], off
	v_addc_co_u32_e32 v3, vcc, 0, v27, vcc
	v_add_co_u32_e32 v80, vcc, 0x403000, v26
	global_load_dwordx4 v[64:67], v[2:3], off offset:3072
	global_load_dwordx4 v[68:71], v[2:3], off offset:2048
	global_load_dwordx4 v[72:75], v[2:3], off offset:1024
	global_load_dwordx4 v[76:79], v[2:3], off
	v_addc_co_u32_e32 v81, vcc, 0, v27, vcc
	v_add_co_u32_e32 v26, vcc, 0x402000, v26
	global_load_dwordx4 v[0:3], v[80:81], off offset:3072
	global_load_dwordx4 v[4:7], v[80:81], off offset:2048
	global_load_dwordx4 v[8:11], v[80:81], off offset:1024
	s_nop 0
	global_load_dwordx4 v[80:83], v[80:81], off
	v_addc_co_u32_e32 v27, vcc, 0, v27, vcc
	v_add_co_u32_e32 v100, vcc, 0x190e0000, v24
	global_load_dwordx4 v[84:87], v[26:27], off offset:3072
	global_load_dwordx4 v[88:91], v[26:27], off offset:2048
	global_load_dwordx4 v[92:95], v[26:27], off offset:1024
	global_load_dwordx4 v[96:99], v[26:27], off
	v_addc_co_u32_e32 v101, vcc, 0, v25, vcc
	v_add_co_u32_e32 v26, vcc, 0x190c0000, v24
	v_lshl_add_u64 v[28:29], s[34:35], 0, v[14:15]
	s_nop 0
	v_addc_co_u32_e32 v27, vcc, 0, v25, vcc
	v_add_co_u32_e32 v108, vcc, 0x190a0000, v24
	global_load_dwordx4 v[100:103], v[100:101], off
	s_nop 0
	global_load_dwordx4 v[104:107], v[26:27], off
	v_addc_co_u32_e32 v109, vcc, 0, v25, vcc
	v_add_co_u32_e32 v26, vcc, 0x19080000, v24
	v_add_co_u32_e64 v162, s[0:1], s29, v28
	s_nop 0
	v_addc_co_u32_e32 v27, vcc, 0, v25, vcc
	v_add_co_u32_e32 v116, vcc, 0x19060000, v24
	global_load_dwordx4 v[108:111], v[108:109], off
	s_nop 0
	global_load_dwordx4 v[112:115], v[26:27], off
	v_addc_co_u32_e32 v117, vcc, 0, v25, vcc
	v_add_co_u32_e32 v26, vcc, 0x19040000, v24
	v_addc_co_u32_e64 v163, s[0:1], 0, v29, s[0:1]
	s_nop 0
	v_addc_co_u32_e32 v27, vcc, 0, v25, vcc
	v_add_co_u32_e32 v124, vcc, 0x19020000, v24
	global_load_dwordx4 v[116:119], v[116:117], off
	s_nop 0
	global_load_dwordx4 v[120:123], v[26:27], off
	v_addc_co_u32_e32 v125, vcc, 0, v25, vcc
	v_add_co_u32_e32 v26, vcc, 0x19000000, v24
	v_add_co_u32_e64 v164, s[0:1], s30, v28
	s_nop 0
	v_addc_co_u32_e32 v27, vcc, 0, v25, vcc
	v_add_co_u32_e32 v132, vcc, 0x191e0000, v24
	global_load_dwordx4 v[124:127], v[124:125], off
	s_nop 0
	global_load_dwordx4 v[128:131], v[26:27], off
	v_addc_co_u32_e32 v133, vcc, 0, v25, vcc
	v_add_co_u32_e32 v26, vcc, 0x191c0000, v24
	v_addc_co_u32_e64 v165, s[0:1], 0, v29, s[0:1]
	s_nop 0
	v_addc_co_u32_e32 v27, vcc, 0, v25, vcc
	v_add_co_u32_e32 v140, vcc, 0x191a0000, v24
	global_load_dwordx4 v[132:135], v[132:133], off
	s_nop 0
	global_load_dwordx4 v[136:139], v[26:27], off
	v_addc_co_u32_e32 v141, vcc, 0, v25, vcc
	v_add_co_u32_e32 v26, vcc, 0x19180000, v24
	v_add_co_u32_e64 v166, s[0:1], s31, v28
	s_nop 0
	v_addc_co_u32_e32 v27, vcc, 0, v25, vcc
	v_add_co_u32_e32 v150, vcc, 0x19160000, v24
	global_load_dwordx4 v[140:143], v[140:141], off
	s_nop 0
	global_load_dwordx4 v[146:149], v[26:27], off
	v_addc_co_u32_e32 v151, vcc, 0, v25, vcc
	v_add_co_u32_e32 v26, vcc, 0x19140000, v24
	v_addc_co_u32_e64 v167, s[0:1], 0, v29, s[0:1]
	s_nop 0
	v_addc_co_u32_e32 v27, vcc, 0, v25, vcc
	v_add_co_u32_e32 v158, vcc, 0x19120000, v24
	global_load_dwordx4 v[150:153], v[150:151], off
	s_nop 0
	global_load_dwordx4 v[154:157], v[26:27], off
	v_addc_co_u32_e32 v159, vcc, 0, v25, vcc
	v_add_co_u32_e32 v160, vcc, 0x19100000, v24
	v_add_co_u32_e64 v168, s[0:1], s37, v28
	s_nop 0
	v_addc_co_u32_e32 v161, vcc, 0, v25, vcc
	global_load_dwordx4 v[24:27], v[158:159], off
	s_nop 0
	global_load_dwordx4 v[158:161], v[160:161], off
	v_addc_co_u32_e64 v169, s[0:1], 0, v29, s[0:1]
	v_add_co_u32_e64 v170, s[0:1], s39, v28
	s_waitcnt vmcnt(24)
	s_waitcnt vmcnt(16)
	s_waitcnt vmcnt(8)
	v_addc_co_u32_e64 v171, s[0:1], 0, v29, s[0:1]
	v_add_co_u32_e64 v172, s[0:1], s46, v28
	v_pk_fma_f32 v[22:23], v[22:23], v[78:79], v[130:131]
	s_nop 0
	v_addc_co_u32_e64 v173, s[0:1], 0, v29, s[0:1]
	v_pk_fma_f32 v[20:21], v[20:21], v[76:77], v[128:129]
	v_add_co_u32_e64 v174, s[0:1], s47, v28
	v_bfe_u32 v12, v20, 16, 1
	v_bfe_u32 v47, v21, 16, 1
	v_bfe_u32 v76, v22, 16, 1
	v_bfe_u32 v77, v23, 16, 1
	v_pk_fma_f32 v[74:75], v[74:75], v[22:23], v[126:127]
	v_pk_fma_f32 v[72:73], v[72:73], v[20:21], v[124:125]
	v_addc_co_u32_e64 v175, s[0:1], 0, v29, s[0:1]
	v_add3_u32 v12, v20, v12, s21
	v_add3_u32 v47, v21, v47, s21
	v_add3_u32 v76, v22, v76, s21
	v_add3_u32 v77, v23, v77, s21
	v_bfe_u32 v78, v72, 16, 1
	v_bfe_u32 v79, v73, 16, 1
	v_bfe_u32 v124, v74, 16, 1
	v_bfe_u32 v125, v75, 16, 1
	v_pk_fma_f32 v[20:21], v[70:71], v[74:75], v[122:123]
	v_pk_fma_f32 v[22:23], v[68:69], v[72:73], v[120:121]
	v_add_co_u32_e64 v44, s[0:1], s48, v28
	v_lshrrev_b32_e32 v12, 16, v12
	v_lshrrev_b32_e32 v69, 16, v76
	v_add3_u32 v70, v72, v78, s21
	v_add3_u32 v71, v73, v79, s21
	v_add3_u32 v72, v74, v124, s21
	v_add3_u32 v73, v75, v125, s21
	v_bfe_u32 v74, v22, 16, 1
	v_bfe_u32 v75, v23, 16, 1
	v_bfe_u32 v76, v20, 16, 1
	v_bfe_u32 v78, v21, 16, 1
	v_pk_fma_f32 v[66:67], v[66:67], v[20:21], v[118:119]
	v_pk_fma_f32 v[64:65], v[64:65], v[22:23], v[116:117]
	v_addc_co_u32_e64 v45, s[0:1], 0, v29, s[0:1]
	v_and_or_b32 v68, v47, s28, v12
	v_and_or_b32 v69, v77, s28, v69
	v_lshrrev_b32_e32 v12, 16, v70
	v_lshrrev_b32_e32 v47, 16, v72
	v_add3_u32 v70, v22, v74, s21
	v_add3_u32 v72, v23, v75, s21
	v_add3_u32 v74, v20, v76, s21
	v_add3_u32 v75, v21, v78, s21
	v_bfe_u32 v76, v64, 16, 1
	v_bfe_u32 v77, v65, 16, 1
	v_bfe_u32 v78, v66, 16, 1
	v_bfe_u32 v79, v67, 16, 1
	v_pk_fma_f32 v[20:21], v[62:63], v[66:67], v[114:115]
	v_pk_fma_f32 v[22:23], v[60:61], v[64:65], v[112:113]
	v_add_co_u32_e64 v42, s[0:1], s49, v28
	s_waitcnt vmcnt(0)
; __device__ __forceinline__ unsigned pk2(float lo, float hi) { return f2bf(lo) | (f2bf(hi) << 16); }
; __device__ __forceinline__ void gla_scan(const float* UPD, const float* DEC, bf16* ST, int gtid, int gthreads) {
;     ...
;             for (int i = 0; i < 16; ++i) {
;                 const size_t unit = (size_t)((c0 + i) * 4 + h);
;                 s = dv[i] * s + uv[i];
;                 u32x2 w; w.x = pk2(s[0], s[1]); w.y = pk2(s[2], s[3]);
;                 *(u32x2*)(ST + unit * 8192 + v * 64 + 4 * kq) = w;
	global_store_dwordx2 v[162:163], v[68:69], off sc1
	v_and_or_b32 v60, v71, s28, v12
	v_and_or_b32 v61, v73, s28, v47
	v_lshrrev_b32_e32 v12, 16, v70
	v_lshrrev_b32_e32 v47, 16, v74
	v_add3_u32 v62, v64, v76, s21
	v_add3_u32 v63, v65, v77, s21
	v_add3_u32 v64, v66, v78, s21
	v_add3_u32 v65, v67, v79, s21
	v_bfe_u32 v66, v22, 16, 1
	v_bfe_u32 v67, v23, 16, 1
	v_bfe_u32 v68, v20, 16, 1
	v_bfe_u32 v69, v21, 16, 1
	v_pk_fma_f32 v[58:59], v[58:59], v[20:21], v[110:111]
	v_pk_fma_f32 v[56:57], v[56:57], v[22:23], v[108:109]
	v_addc_co_u32_e64 v43, s[0:1], 0, v29, s[0:1]
	global_store_dwordx2 v[164:165], v[60:61], off sc1
	v_and_or_b32 v60, v72, s28, v12
	v_and_or_b32 v61, v75, s28, v47
	v_lshrrev_b32_e32 v12, 16, v62
	v_lshrrev_b32_e32 v47, 16, v64
	v_add3_u32 v62, v22, v66, s21
	v_add3_u32 v64, v23, v67, s21
	v_add3_u32 v66, v20, v68, s21
	v_add3_u32 v67, v21, v69, s21
	v_bfe_u32 v68, v56, 16, 1
	v_bfe_u32 v69, v57, 16, 1
	v_bfe_u32 v70, v58, 16, 1
	v_bfe_u32 v71, v59, 16, 1
	v_pk_fma_f32 v[20:21], v[54:55], v[58:59], v[106:107]
	v_pk_fma_f32 v[22:23], v[52:53], v[56:57], v[104:105]
	v_add_co_u32_e64 v40, s[0:1], s56, v28
	global_store_dwordx2 v[166:167], v[60:61], off sc1
	v_and_or_b32 v52, v63, s28, v12
	v_and_or_b32 v53, v65, s28, v47
	v_lshrrev_b32_e32 v12, 16, v62
	v_lshrrev_b32_e32 v47, 16, v66
	v_add3_u32 v54, v56, v68, s21
	v_add3_u32 v55, v57, v69, s21
	v_add3_u32 v56, v58, v70, s21
	v_add3_u32 v57, v59, v71, s21
	v_bfe_u32 v58, v22, 16, 1
	v_bfe_u32 v59, v23, 16, 1
	v_bfe_u32 v60, v20, 16, 1
	v_bfe_u32 v61, v21, 16, 1
	v_pk_fma_f32 v[50:51], v[50:51], v[20:21], v[102:103]
	v_pk_fma_f32 v[48:49], v[48:49], v[22:23], v[100:101]
	v_addc_co_u32_e64 v41, s[0:1], 0, v29, s[0:1]
	global_store_dwordx2 v[168:169], v[52:53], off sc1
	v_and_or_b32 v52, v64, s28, v12
	v_and_or_b32 v53, v67, s28, v47
	v_lshrrev_b32_e32 v12, 16, v54
	v_lshrrev_b32_e32 v47, 16, v56
	v_add3_u32 v54, v22, v58, s21
	v_add3_u32 v56, v23, v59, s21
	v_add3_u32 v58, v20, v60, s21
	v_add3_u32 v59, v21, v61, s21
	v_bfe_u32 v60, v48, 16, 1
	v_bfe_u32 v61, v49, 16, 1
	v_bfe_u32 v62, v50, 16, 1
	v_pk_fma_f32 v[20:21], v[98:99], v[50:51], v[160:161]
	v_pk_fma_f32 v[22:23], v[96:97], v[48:49], v[158:159]
	v_add_co_u32_e64 v38, s[0:1], s57, v28
	v_bfe_u32 v63, v51, 16, 1
	global_store_dwordx2 v[170:171], v[52:53], off sc1
	v_and_or_b32 v52, v55, s28, v12
	v_and_or_b32 v53, v57, s28, v47
	v_lshrrev_b32_e32 v12, 16, v54
	v_lshrrev_b32_e32 v47, 16, v58
	v_add3_u32 v54, v48, v60, s21
	v_add3_u32 v55, v49, v61, s21
	v_add3_u32 v50, v50, v62, s21
	v_bfe_u32 v57, v22, 16, 1
	v_bfe_u32 v58, v23, 16, 1
	v_bfe_u32 v60, v20, 16, 1
	v_bfe_u32 v61, v21, 16, 1
	v_pk_fma_f32 v[26:27], v[94:95], v[20:21], v[26:27]
	v_pk_fma_f32 v[24:25], v[92:93], v[22:23], v[24:25]
	v_addc_co_u32_e64 v39, s[0:1], 0, v29, s[0:1]
	v_add3_u32 v51, v51, v63, s21
	global_store_dwordx2 v[172:173], v[52:53], off sc1
	v_and_or_b32 v48, v56, s28, v12
	v_and_or_b32 v49, v59, s28, v47
	v_lshrrev_b32_e32 v12, 16, v54
	v_lshrrev_b32_e32 v47, 16, v50
	v_add3_u32 v50, v22, v57, s21
	v_add3_u32 v52, v23, v58, s21
	v_add3_u32 v53, v20, v60, s21
	v_add3_u32 v54, v21, v61, s21
	v_bfe_u32 v56, v24, 16, 1
	v_bfe_u32 v57, v25, 16, 1
	v_bfe_u32 v58, v26, 16, 1
	v_bfe_u32 v59, v27, 16, 1
	v_pk_fma_f32 v[20:21], v[90:91], v[26:27], v[156:157]
	v_pk_fma_f32 v[22:23], v[88:89], v[24:25], v[154:155]
	v_add_co_u32_e64 v36, s[0:1], s58, v28
	global_store_dwordx2 v[174:175], v[48:49], off sc1
	v_and_or_b32 v48, v55, s28, v12
	v_and_or_b32 v49, v51, s28, v47
	v_lshrrev_b32_e32 v12, 16, v50
	v_lshrrev_b32_e32 v47, 16, v53
	v_add3_u32 v50, v24, v56, s21
	v_add3_u32 v51, v25, v57, s21
	v_add3_u32 v53, v26, v58, s21
	v_add3_u32 v55, v27, v59, s21
	v_bfe_u32 v56, v22, 16, 1
	v_bfe_u32 v57, v23, 16, 1
	v_bfe_u32 v58, v20, 16, 1
	v_bfe_u32 v59, v21, 16, 1
	v_pk_fma_f32 v[24:25], v[86:87], v[20:21], v[152:153]
; __device__ __forceinline__ unsigned pk2(float lo, float hi) { return f2bf(lo) | (f2bf(hi) << 16); }
; __device__ __forceinline__ void gla_scan(const float* UPD, const float* DEC, bf16* ST, int gtid, int gthreads) {
;     for (int p = gtid; p < 4 * 128 * 16; p += gthreads) {
;         const int h = p >> 11, rem = p & 2047, v = rem >> 4, kq = rem & 15;
;         f32x4 s = (f32x4){0.f, 0.f, 0.f, 0.f};
; #pragma unroll 1
;         for (int c0 = 0; c0 < 64; c0 += 16) {
;             f32x4 dv[16], uv[16];
; #pragma unroll
;             for (int i = 0; i < 16; ++i) { const size_t unit = (size_t)((c0 + i) * 4 + h); dv[i] = *(const f32x4*)(DEC + unit * 64 + 4 * kq); uv[i] = *(const f32x4*)(UPD + unit * 8192 + v * 64 + 4 * kq); }
;             asm volatile("" : "+v"(dv[0]), "+v"(dv[1]), "+v"(dv[2]), "+v"(dv[3]), "+v"(dv[4]), "+v"(dv[5]), "+v"(dv[6]), "+v"(dv[7]) :: "memory");
;             asm volatile("" : "+v"(dv[8]), "+v"(dv[9]), "+v"(dv[10]), "+v"(dv[11]), "+v"(dv[12]), "+v"(dv[13]), "+v"(dv[14]), "+v"(dv[15]) :: "memory");
;             asm volatile("" : "+v"(uv[0]), "+v"(uv[1]), "+v"(uv[2]), "+v"(uv[3]), "+v"(uv[4]), "+v"(uv[5]), "+v"(uv[6]), "+v"(uv[7]) :: "memory");
;             asm volatile("" : "+v"(uv[8]), "+v"(uv[9]), "+v"(uv[10]), "+v"(uv[11]), "+v"(uv[12]), "+v"(uv[13]), "+v"(uv[14]), "+v"(uv[15]) :: "memory");
; #pragma unroll
;             for (int i = 0; i < 16; ++i) {
;                 const size_t unit = (size_t)((c0 + i) * 4 + h);
;                 s = dv[i] * s + uv[i];
;                 u32x2 w; w.x = pk2(s[0], s[1]); w.y = pk2(s[2], s[3]);
;                 *(u32x2*)(ST + unit * 8192 + v * 64 + 4 * kq) = w;
;             }
	v_pk_fma_f32 v[26:27], v[84:85], v[22:23], v[150:151]
	v_addc_co_u32_e64 v37, s[0:1], 0, v29, s[0:1]
	global_store_dwordx2 v[44:45], v[48:49], off sc1
	v_and_or_b32 v44, v52, s28, v12
	v_and_or_b32 v45, v54, s28, v47
	v_lshrrev_b32_e32 v12, 16, v50
	v_lshrrev_b32_e32 v47, 16, v53
	v_add3_u32 v48, v22, v56, s21
	v_add3_u32 v49, v23, v57, s21
	v_add3_u32 v50, v20, v58, s21
	v_add3_u32 v52, v21, v59, s21
	v_bfe_u32 v53, v26, 16, 1
	v_bfe_u32 v56, v24, 16, 1
	v_pk_fma_f32 v[20:21], v[82:83], v[24:25], v[148:149]
	v_pk_fma_f32 v[22:23], v[80:81], v[26:27], v[146:147]
	v_add_co_u32_e64 v34, s[0:1], s59, v28
	v_bfe_u32 v54, v27, 16, 1
	v_bfe_u32 v57, v25, 16, 1
	global_store_dwordx2 v[42:43], v[44:45], off sc1
	v_and_or_b32 v42, v51, s28, v12
	v_and_or_b32 v43, v55, s28, v47
	v_lshrrev_b32_e32 v12, 16, v48
	v_lshrrev_b32_e32 v44, 16, v50
	v_add3_u32 v26, v26, v53, s21
	v_add3_u32 v45, v24, v56, s21
	v_bfe_u32 v48, v22, 16, 1
	v_bfe_u32 v50, v23, 16, 1
	v_bfe_u32 v51, v20, 16, 1
	v_bfe_u32 v53, v21, 16, 1
	v_pk_fma_f32 v[10:11], v[10:11], v[20:21], v[142:143]
	v_pk_fma_f32 v[8:9], v[8:9], v[22:23], v[140:141]
	v_addc_co_u32_e64 v35, s[0:1], 0, v29, s[0:1]
	v_add3_u32 v27, v27, v54, s21
	v_add3_u32 v47, v25, v57, s21
	global_store_dwordx2 v[40:41], v[42:43], off sc1
	v_and_or_b32 v24, v49, s28, v12
	v_and_or_b32 v25, v52, s28, v44
	v_lshrrev_b32_e32 v12, 16, v26
	v_lshrrev_b32_e32 v26, 16, v45
	v_add3_u32 v22, v22, v48, s21
	v_add3_u32 v40, v23, v50, s21
	v_add3_u32 v20, v20, v51, s21
	v_add3_u32 v41, v21, v53, s21
	v_bfe_u32 v21, v8, 16, 1
	v_bfe_u32 v23, v9, 16, 1
	v_bfe_u32 v42, v10, 16, 1
	v_pk_fma_f32 v[6:7], v[6:7], v[10:11], v[138:139]
	v_pk_fma_f32 v[4:5], v[4:5], v[8:9], v[136:137]
	v_add_co_u32_e64 v32, s[0:1], s64, v28
	v_bfe_u32 v43, v11, 16, 1
	global_store_dwordx2 v[38:39], v[24:25], off sc1
	v_and_or_b32 v24, v27, s28, v12
	v_and_or_b32 v25, v47, s28, v26
	v_lshrrev_b32_e32 v12, 16, v22
	v_lshrrev_b32_e32 v26, 16, v20
	v_add3_u32 v8, v8, v21, s21
	v_add3_u32 v9, v9, v23, s21
	v_add3_u32 v10, v10, v42, s21
	v_bfe_u32 v27, v4, 16, 1
	v_bfe_u32 v39, v6, 16, 1
	v_pk_fma_f32 v[22:23], v[2:3], v[6:7], v[134:135]
	v_pk_fma_f32 v[20:21], v[0:1], v[4:5], v[132:133]
	v_addc_co_u32_e64 v33, s[0:1], 0, v29, s[0:1]
	v_add3_u32 v11, v11, v43, s21
	v_bfe_u32 v38, v5, 16, 1
	v_bfe_u32 v42, v7, 16, 1
	v_and_or_b32 v0, v40, s28, v12
	v_and_or_b32 v1, v41, s28, v26
	v_lshrrev_b32_e32 v2, 16, v8
	v_lshrrev_b32_e32 v3, 16, v10
	v_add3_u32 v4, v4, v27, s21
	v_add3_u32 v6, v6, v39, s21
	v_bfe_u32 v8, v20, 16, 1
	v_bfe_u32 v12, v22, 16, 1
	v_add_co_u32_e64 v30, s[0:1], s65, v28
	global_store_dwordx2 v[36:37], v[24:25], off sc1
	v_add3_u32 v5, v5, v38, s21
	v_add3_u32 v7, v7, v42, s21
	v_bfe_u32 v10, v21, 16, 1
	v_bfe_u32 v24, v23, 16, 1
	global_store_dwordx2 v[34:35], v[0:1], off sc1
	v_and_or_b32 v0, v9, s28, v2
	v_and_or_b32 v1, v11, s28, v3
	v_lshrrev_b32_e32 v2, 16, v4
	v_lshrrev_b32_e32 v3, 16, v6
	v_add3_u32 v4, v20, v8, s21
	v_add3_u32 v8, v22, v12, s21
	s_add_i32 s67, s67, 16
	v_addc_co_u32_e64 v31, s[0:1], 0, v29, s[0:1]
	v_add_co_u32_e32 v28, vcc, 0x1d0f0000, v28
	v_add3_u32 v6, v21, v10, s21
	v_add3_u32 v9, v23, v24, s21
	global_store_dwordx2 v[32:33], v[0:1], off sc1
	v_and_or_b32 v0, v5, s28, v2
	v_and_or_b32 v1, v7, s28, v3
	v_lshrrev_b32_e32 v2, 16, v4
	v_lshrrev_b32_e32 v3, 16, v8
	v_lshl_add_u64 v[14:15], v[14:15], 0, s[12:13]
	v_lshl_add_u64 v[16:17], v[16:17], 0, s[14:15]
	v_lshl_add_u64 v[18:19], v[18:19], 0, s[16:17]
	s_cmp_gt_u32 s67, 47
	v_addc_co_u32_e32 v29, vcc, 0, v29, vcc
	global_store_dwordx2 v[30:31], v[0:1], off sc1
	v_and_or_b32 v0, v6, s28, v2
	v_and_or_b32 v1, v9, s28, v3
	global_store_dwordx2 v[28:29], v[0:1], off sc1
	s_cbranch_scc0 .LBB0_1106
	v_add_u32_e32 v203, s11, v203
	v_cmp_lt_i32_e32 vcc, s66, v203
	s_or_b64 s[6:7], vcc, s[6:7]
	v_add_u32_e32 v46, s20, v46
	s_andn2_b64 exec, exec, s[6:7]
	s_cbranch_execnz .LBB0_1105

; __device__ __forceinline__ float ss_val(u64 v) { return (float)v * (1.0f / 1099511627776.0f); }
; __global__ void __launch_bounds__(NTHREADS, 2) fwd(Args a) {
;     ...
;                 const float rs = __builtin_amdgcn_rsqf(ss_val(sv[r2]) * (1.f / D) + EPS);
;                 f32x4* orow = (f32x4*)(outb + (size_t)(r2 ? m1 : m) * D);
; #pragma unroll
;                 for (int j = 0; j < 2; ++j) {
;                     const u32x4 x4 = xv[r2][j]; const f32x4 w0 = wv[j][0], w1 = wv[j][1];
;                     f32x4 o0, o1;
;                     o0[0] = bf_lo(x4[0]) * rs * w0[0]; o0[1] = bf_hi(x4[0]) * rs * w0[1]; o0[2] = bf_lo(x4[1]) * rs * w0[2]; o0[3] = bf_hi(x4[1]) * rs * w0[3];
;                     o1[0] = bf_lo(x4[2]) * rs * w1[0]; o1[1] = bf_hi(x4[2]) * rs * w1[1]; o1[2] = bf_lo(x4[3]) * rs * w1[2]; o1[3] = bf_hi(x4[3]) * rs * w1[3];
;                     orow[2 * (lane + 64 * j)] = o0; orow[2 * (lane + 64 * j) + 1] = o1;
.Lfn_a_p:
	s_lshl_b32 s18, s38, 12
	s_add_u32 s18, s4, s18
	s_addc_u32 s19, s5, 0
	v_cvt_f32_u32_e32 v66, v24
	v_cvt_f32_u32_e32 v67, v25
	v_fmamk_f32 v66, v67, 0x4f800000, v66
	v_fmamk_f32 v66, v66, 0x26800000, v4
	v_rsq_f32_e32 v64, v66
	v_lshlrev_b32_e32 v60, 16, v26
	v_and_b32_e32 v61, 0xffff0000, v26
	v_lshlrev_b32_e32 v62, 16, v27
	v_and_b32_e32 v63, 0xffff0000, v27
	v_pk_mul_f32 v[60:61], v[64:65], v[60:61] op_sel_hi:[0,1]
	v_pk_mul_f32 v[62:63], v[64:65], v[62:63] op_sel_hi:[0,1]
	v_pk_mul_f32 v[68:69], v[8:9], v[60:61]
	v_pk_mul_f32 v[70:71], v[10:11], v[62:63]
	global_store_dwordx4 v3, v[68:71], s[18:19] offset:0 sc1 nt
	v_lshlrev_b32_e32 v60, 16, v28
	v_and_b32_e32 v61, 0xffff0000, v28
	v_lshlrev_b32_e32 v62, 16, v29
	v_and_b32_e32 v63, 0xffff0000, v29
	v_pk_mul_f32 v[60:61], v[64:65], v[60:61] op_sel_hi:[0,1]
	v_pk_mul_f32 v[62:63], v[64:65], v[62:63] op_sel_hi:[0,1]
	v_pk_mul_f32 v[72:73], v[12:13], v[60:61]
	v_pk_mul_f32 v[74:75], v[14:15], v[62:63]
	global_store_dwordx4 v3, v[72:75], s[18:19] offset:1024 sc1 nt
	v_lshlrev_b32_e32 v60, 16, v30
	v_and_b32_e32 v61, 0xffff0000, v30
	v_lshlrev_b32_e32 v62, 16, v31
	v_and_b32_e32 v63, 0xffff0000, v31
	v_pk_mul_f32 v[60:61], v[64:65], v[60:61] op_sel_hi:[0,1]
	v_pk_mul_f32 v[62:63], v[64:65], v[62:63] op_sel_hi:[0,1]
	v_pk_mul_f32 v[76:77], v[16:17], v[60:61]
	v_pk_mul_f32 v[78:79], v[18:19], v[62:63]
	global_store_dwordx4 v3, v[76:79], s[18:19] offset:2048 sc1 nt
	v_lshlrev_b32_e32 v60, 16, v32
	v_and_b32_e32 v61, 0xffff0000, v32
	v_lshlrev_b32_e32 v62, 16, v33
	v_and_b32_e32 v63, 0xffff0000, v33
	v_pk_mul_f32 v[60:61], v[64:65], v[60:61] op_sel_hi:[0,1]
	v_pk_mul_f32 v[62:63], v[64:65], v[62:63] op_sel_hi:[0,1]
	v_pk_mul_f32 v[80:81], v[20:21], v[60:61]
	v_pk_mul_f32 v[82:83], v[22:23], v[62:63]
	global_store_dwordx4 v3, v[80:83], s[18:19] offset:3072 sc1 nt
	s_add_u32 s38, s38, s36
	s_cmp_lt_u32 s38, 0x1000
	s_cbranch_scc0 .LBB0_1445

; __device__ __forceinline__ float ss_val(u64 v) { return (float)v * (1.0f / 1099511627776.0f); }
; __global__ void __launch_bounds__(NTHREADS, 2) fwd(Args a) {
;     ...
;                 const float rs = __builtin_amdgcn_rsqf(ss_val(sv[r2]) * (1.f / D) + EPS);
;                 f32x4* orow = (f32x4*)(outb + (size_t)(r2 ? m1 : m) * D);
; #pragma unroll
;                 for (int j = 0; j < 2; ++j) {
;                     const u32x4 x4 = xv[r2][j]; const f32x4 w0 = wv[j][0], w1 = wv[j][1];
;                     f32x4 o0, o1;
;                     o0[0] = bf_lo(x4[0]) * rs * w0[0]; o0[1] = bf_hi(x4[0]) * rs * w0[1]; o0[2] = bf_lo(x4[1]) * rs * w0[2]; o0[3] = bf_hi(x4[1]) * rs * w0[3];
;                     o1[0] = bf_lo(x4[2]) * rs * w1[0]; o1[1] = bf_hi(x4[2]) * rs * w1[1]; o1[2] = bf_lo(x4[3]) * rs * w1[2]; o1[3] = bf_hi(x4[3]) * rs * w1[3];
;                     orow[2 * (lane + 64 * j)] = o0; orow[2 * (lane + 64 * j) + 1] = o1;
.Lfn_b_p:
	s_lshl_b32 s18, s38, 12
	s_add_u32 s18, s4, s18
	s_addc_u32 s19, s5, 0
	v_cvt_f32_u32_e32 v66, v36
	v_cvt_f32_u32_e32 v67, v37
	v_fmamk_f32 v66, v67, 0x4f800000, v66
	v_fmamk_f32 v66, v66, 0x26800000, v4
	v_rsq_f32_e32 v64, v66
	v_lshlrev_b32_e32 v60, 16, v38
	v_and_b32_e32 v61, 0xffff0000, v38
	v_lshlrev_b32_e32 v62, 16, v39
	v_and_b32_e32 v63, 0xffff0000, v39
	v_pk_mul_f32 v[60:61], v[64:65], v[60:61] op_sel_hi:[0,1]
	v_pk_mul_f32 v[62:63], v[64:65], v[62:63] op_sel_hi:[0,1]
	v_pk_mul_f32 v[68:69], v[8:9], v[60:61]
	v_pk_mul_f32 v[70:71], v[10:11], v[62:63]
	global_store_dwordx4 v3, v[68:71], s[18:19] offset:0 sc1 nt
	v_lshlrev_b32_e32 v60, 16, v40
	v_and_b32_e32 v61, 0xffff0000, v40
	v_lshlrev_b32_e32 v62, 16, v41
	v_and_b32_e32 v63, 0xffff0000, v41
	v_pk_mul_f32 v[60:61], v[64:65], v[60:61] op_sel_hi:[0,1]
	v_pk_mul_f32 v[62:63], v[64:65], v[62:63] op_sel_hi:[0,1]
	v_pk_mul_f32 v[72:73], v[12:13], v[60:61]
	v_pk_mul_f32 v[74:75], v[14:15], v[62:63]
	global_store_dwordx4 v3, v[72:75], s[18:19] offset:1024 sc1 nt
	v_lshlrev_b32_e32 v60, 16, v42
	v_and_b32_e32 v61, 0xffff0000, v42
	v_lshlrev_b32_e32 v62, 16, v43
	v_and_b32_e32 v63, 0xffff0000, v43
	v_pk_mul_f32 v[60:61], v[64:65], v[60:61] op_sel_hi:[0,1]
	v_pk_mul_f32 v[62:63], v[64:65], v[62:63] op_sel_hi:[0,1]
	v_pk_mul_f32 v[76:77], v[16:17], v[60:61]
	v_pk_mul_f32 v[78:79], v[18:19], v[62:63]
	global_store_dwordx4 v3, v[76:79], s[18:19] offset:2048 sc1 nt
	v_lshlrev_b32_e32 v60, 16, v44
	v_and_b32_e32 v61, 0xffff0000, v44
	v_lshlrev_b32_e32 v62, 16, v45
	v_and_b32_e32 v63, 0xffff0000, v45
	v_pk_mul_f32 v[60:61], v[64:65], v[60:61] op_sel_hi:[0,1]
	v_pk_mul_f32 v[62:63], v[64:65], v[62:63] op_sel_hi:[0,1]
	v_pk_mul_f32 v[80:81], v[20:21], v[60:61]
	v_pk_mul_f32 v[82:83], v[22:23], v[62:63]
	global_store_dwordx4 v3, v[80:83], s[18:19] offset:3072 sc1 nt
	s_add_u32 s38, s38, s36
	s_cmp_lt_u32 s38, 0x1000
	s_cbranch_scc0 .LBB0_1445

; __device__ __forceinline__ float ss_val(u64 v) { return (float)v * (1.0f / 1099511627776.0f); }
; __global__ void __launch_bounds__(NTHREADS, 2) fwd(Args a) {
;     ...
;                 const float rs = __builtin_amdgcn_rsqf(ss_val(sv[r2]) * (1.f / D) + EPS);
;                 f32x4* orow = (f32x4*)(outb + (size_t)(r2 ? m1 : m) * D);
; #pragma unroll
;                 for (int j = 0; j < 2; ++j) {
;                     const u32x4 x4 = xv[r2][j]; const f32x4 w0 = wv[j][0], w1 = wv[j][1];
;                     f32x4 o0, o1;
;                     o0[0] = bf_lo(x4[0]) * rs * w0[0]; o0[1] = bf_hi(x4[0]) * rs * w0[1]; o0[2] = bf_lo(x4[1]) * rs * w0[2]; o0[3] = bf_hi(x4[1]) * rs * w0[3];
;                     o1[0] = bf_lo(x4[2]) * rs * w1[0]; o1[1] = bf_hi(x4[2]) * rs * w1[1]; o1[2] = bf_lo(x4[3]) * rs * w1[2]; o1[3] = bf_hi(x4[3]) * rs * w1[3];
;                     orow[2 * (lane + 64 * j)] = o0; orow[2 * (lane + 64 * j) + 1] = o1;
.Lfn_c_p:
	s_lshl_b32 s18, s38, 12
	s_add_u32 s18, s4, s18
	s_addc_u32 s19, s5, 0
	v_cvt_f32_u32_e32 v66, v48
	v_cvt_f32_u32_e32 v67, v49
	v_fmamk_f32 v66, v67, 0x4f800000, v66
	v_fmamk_f32 v66, v66, 0x26800000, v4
	v_rsq_f32_e32 v64, v66
	v_lshlrev_b32_e32 v60, 16, v50
	v_and_b32_e32 v61, 0xffff0000, v50
	v_lshlrev_b32_e32 v62, 16, v51
	v_and_b32_e32 v63, 0xffff0000, v51
	v_pk_mul_f32 v[60:61], v[64:65], v[60:61] op_sel_hi:[0,1]
	v_pk_mul_f32 v[62:63], v[64:65], v[62:63] op_sel_hi:[0,1]
	v_pk_mul_f32 v[68:69], v[8:9], v[60:61]
	v_pk_mul_f32 v[70:71], v[10:11], v[62:63]
	global_store_dwordx4 v3, v[68:71], s[18:19] offset:0 sc1 nt
	v_lshlrev_b32_e32 v60, 16, v52
	v_and_b32_e32 v61, 0xffff0000, v52
	v_lshlrev_b32_e32 v62, 16, v53
	v_and_b32_e32 v63, 0xffff0000, v53
	v_pk_mul_f32 v[60:61], v[64:65], v[60:61] op_sel_hi:[0,1]
	v_pk_mul_f32 v[62:63], v[64:65], v[62:63] op_sel_hi:[0,1]
	v_pk_mul_f32 v[72:73], v[12:13], v[60:61]
	v_pk_mul_f32 v[74:75], v[14:15], v[62:63]
	global_store_dwordx4 v3, v[72:75], s[18:19] offset:1024 sc1 nt
	v_lshlrev_b32_e32 v60, 16, v54
	v_and_b32_e32 v61, 0xffff0000, v54
	v_lshlrev_b32_e32 v62, 16, v55
	v_and_b32_e32 v63, 0xffff0000, v55
	v_pk_mul_f32 v[60:61], v[64:65], v[60:61] op_sel_hi:[0,1]
	v_pk_mul_f32 v[62:63], v[64:65], v[62:63] op_sel_hi:[0,1]
	v_pk_mul_f32 v[76:77], v[16:17], v[60:61]
	v_pk_mul_f32 v[78:79], v[18:19], v[62:63]
	global_store_dwordx4 v3, v[76:79], s[18:19] offset:2048 sc1 nt
	v_lshlrev_b32_e32 v60, 16, v56
	v_and_b32_e32 v61, 0xffff0000, v56
	v_lshlrev_b32_e32 v62, 16, v57
	v_and_b32_e32 v63, 0xffff0000, v57
	v_pk_mul_f32 v[60:61], v[64:65], v[60:61] op_sel_hi:[0,1]
	v_pk_mul_f32 v[62:63], v[64:65], v[62:63] op_sel_hi:[0,1]
	v_pk_mul_f32 v[80:81], v[20:21], v[60:61]
	v_pk_mul_f32 v[82:83], v[22:23], v[62:63]
	global_store_dwordx4 v3, v[80:83], s[18:19] offset:3072 sc1 nt
	s_add_u32 s38, s38, s36
	s_cmp_lt_u32 s38, 0x1000
	s_cbranch_scc0 .LBB0_1445

; __device__ __forceinline__ float ss_val(u64 v) { return (float)v * (1.0f / 1099511627776.0f); }
; __global__ void __launch_bounds__(NTHREADS, 2) fwd(Args a) {
;     ...
;                 const float rs = __builtin_amdgcn_rsqf(ss_val(sv[r2]) * (1.f / D) + EPS);
;                 f32x4* orow = (f32x4*)(outb + (size_t)(r2 ? m1 : m) * D);
; #pragma unroll
;                 for (int j = 0; j < 2; ++j) {
;                     const u32x4 x4 = xv[r2][j]; const f32x4 w0 = wv[j][0], w1 = wv[j][1];
;                     f32x4 o0, o1;
;                     o0[0] = bf_lo(x4[0]) * rs * w0[0]; o0[1] = bf_hi(x4[0]) * rs * w0[1]; o0[2] = bf_lo(x4[1]) * rs * w0[2]; o0[3] = bf_hi(x4[1]) * rs * w0[3];
;                     o1[0] = bf_lo(x4[2]) * rs * w1[0]; o1[1] = bf_hi(x4[2]) * rs * w1[1]; o1[2] = bf_lo(x4[3]) * rs * w1[2]; o1[3] = bf_hi(x4[3]) * rs * w1[3];
;                     orow[2 * (lane + 64 * j)] = o0; orow[2 * (lane + 64 * j) + 1] = o1;
.Lfn_e_p:
	s_lshl_b32 s18, s38, 12
	s_add_u32 s18, s4, s18
	s_addc_u32 s19, s5, 0
	v_cvt_f32_u32_e32 v66, v36
	v_cvt_f32_u32_e32 v67, v37
	v_fmamk_f32 v66, v67, 0x4f800000, v66
	v_fmamk_f32 v66, v66, 0x26800000, v4
	v_rsq_f32_e32 v64, v66
	v_lshlrev_b32_e32 v60, 16, v38
	v_and_b32_e32 v61, 0xffff0000, v38
	v_lshlrev_b32_e32 v62, 16, v39
	v_and_b32_e32 v63, 0xffff0000, v39
	v_pk_mul_f32 v[60:61], v[64:65], v[60:61] op_sel_hi:[0,1]
	v_pk_mul_f32 v[62:63], v[64:65], v[62:63] op_sel_hi:[0,1]
	v_pk_mul_f32 v[68:69], v[8:9], v[60:61]
	v_pk_mul_f32 v[70:71], v[10:11], v[62:63]
	global_store_dwordx4 v3, v[68:71], s[18:19] offset:0 sc1 nt
	v_lshlrev_b32_e32 v60, 16, v40
	v_and_b32_e32 v61, 0xffff0000, v40
	v_lshlrev_b32_e32 v62, 16, v41
	v_and_b32_e32 v63, 0xffff0000, v41
	v_pk_mul_f32 v[60:61], v[64:65], v[60:61] op_sel_hi:[0,1]
	v_pk_mul_f32 v[62:63], v[64:65], v[62:63] op_sel_hi:[0,1]
	v_pk_mul_f32 v[72:73], v[12:13], v[60:61]
	v_pk_mul_f32 v[74:75], v[14:15], v[62:63]
	global_store_dwordx4 v3, v[72:75], s[18:19] offset:1024 sc1 nt
	v_lshlrev_b32_e32 v60, 16, v42
	v_and_b32_e32 v61, 0xffff0000, v42
	v_lshlrev_b32_e32 v62, 16, v43
	v_and_b32_e32 v63, 0xffff0000, v43
	v_pk_mul_f32 v[60:61], v[64:65], v[60:61] op_sel_hi:[0,1]
	v_pk_mul_f32 v[62:63], v[64:65], v[62:63] op_sel_hi:[0,1]
	v_pk_mul_f32 v[76:77], v[16:17], v[60:61]
	v_pk_mul_f32 v[78:79], v[18:19], v[62:63]
	global_store_dwordx4 v3, v[76:79], s[18:19] offset:2048 sc1 nt
	v_lshlrev_b32_e32 v60, 16, v44
	v_and_b32_e32 v61, 0xffff0000, v44
	v_lshlrev_b32_e32 v62, 16, v45
	v_and_b32_e32 v63, 0xffff0000, v45
	v_pk_mul_f32 v[60:61], v[64:65], v[60:61] op_sel_hi:[0,1]
	v_pk_mul_f32 v[62:63], v[64:65], v[62:63] op_sel_hi:[0,1]
	v_pk_mul_f32 v[80:81], v[20:21], v[60:61]
	v_pk_mul_f32 v[82:83], v[22:23], v[62:63]
	global_store_dwordx4 v3, v[80:83], s[18:19] offset:3072 sc1 nt
	s_add_u32 s38, s38, s36
	s_cmp_lt_u32 s38, 0x1000
	s_cbranch_scc0 .LBB0_1445
	s_branch .Lfn_c
